# K-blocked layouts for the outproj operands (mm written blocked by the merge epilogue, woT by the weight prep); outproj stages read contiguous full lines
# baseline (speedup 1.0000x reference)
;   __device__ __forceinline__ const float* x() const { return (const float*)(const __attribute__((address_space(1))) float*)kp[0]; }
;   __device__ __forceinline__ const float* wo() const { return (const float*)(const __attribute__((address_space(1))) float*)kp[15]; }
;   __device__ __forceinline__ half_t* woT() const { return (half_t*)(ws() + OFF_woT); }
; template <class CM>
; __device__ __forceinline__ void tconv_tile(const float* __restrict__ src, int lds_, half_t* __restrict__ dst, int ldd,
;                                            int n0, int k0, CM cmap, char* smem) {
;   float* t = (float*)smem;
;   int tid = threadIdx.x;
;   asm volatile("" : "+v"(tid));
;   {
;     const int n = tid & 63;
;     const int c = cmap(n0 + n);
;     float tv[16];
; #pragma unroll
;     for (int i = 0; i < 16; ++i) {
;       const int k = (tid >> 6) + 4 * i;
;       tv[i] = (c >= 0) ? src[(size_t)(k0 + k) * lds_ + c] : 0.f;
;     }
; #pragma unroll
;     for (int i = 0; i < 16; ++i) {
;       const int k = (tid >> 6) + 4 * i;
;       t[k * 65 + n] = tv[i];
;     }
;   }
;   __syncthreads();
; #pragma unroll
;   for (int i = 0; i < 2; ++i) {
;     const int idx = tid + 256 * i;
;     const int n = idx >> 3, kc = (idx & 7) * 8;
;     h8 v;
; #pragma unroll
;     for (int j = 0; j < 8; ++j) v[j] = (half_t)t[(kc + j) * 65 + n];
;     *(h8*)&dst[(size_t)(n0 + n) * ldd + k0 + kc] = v;
;   }
;   __syncthreads();
; __device__ __forceinline__ void prep_weights(const KP& p, int l, char* smem) {
;     ...
;     } else if (it < 1856 + 384 + 256) {
;       const int j = it - 1856 - 384;
;       const int nt = j >> 4, kt = j & 15;
;       tconv_tile(p.wo() + (size_t)l * DM * DM, DM, p.woT(), DM, nt * 64, kt * 64, [](int n) { return n; }, smem);
.LBB0_40:
	s_andn2_b64 vcc, exec, s[16:17]
	s_cbranch_vccnz .LBB0_42
	s_load_dwordx2 s[16:17], s[2:3], 0x78
	s_lshl_b32 s12, s66, 2
	s_lshl_b32 s18, s66, 6
	v_mov_b32_e32 v24, v224
	s_and_b32 s12, s12, 0x3fc0
	s_and_b32 s18, s18, 0x3c0
	s_addk_i32 s12, 0xdd00
	v_ashrrev_i32_e32 v26, 6, v24
	v_and_b32_e32 v25, 63, v24
	v_add_u32_e32 v6, s18, v26
	v_or_b32_e32 v4, s12, v25
	v_ashrrev_i32_e32 v7, 31, v6
	s_waitcnt lgkmcnt(0)
	v_lshl_add_u64 v[8:9], v[4:5], 2, s[16:17]
	v_lshlrev_b64 v[6:7], 12, v[6:7]
	v_lshl_add_u64 v[6:7], v[8:9], 0, v[6:7]
	v_add_co_u32_e32 v8, vcc, s40, v6
	s_lshr_b32 s16, s18, 5
	s_lshl_b32 s16, s16, 16
	s_nop 0
	v_addc_co_u32_e32 v9, vcc, 0, v7, vcc
	v_add_co_u32_e32 v10, vcc, s44, v6
	s_add_u32 s16, s28, s16
	s_nop 0
	v_addc_co_u32_e32 v11, vcc, 0, v7, vcc
	v_add_co_u32_e32 v12, vcc, s45, v6
	s_addc_u32 s17, s29, 0
	s_nop 0
	v_addc_co_u32_e32 v13, vcc, 0, v7, vcc
	v_add_co_u32_e32 v16, vcc, s46, v6
	s_nop 1
	v_addc_co_u32_e32 v17, vcc, 0, v7, vcc
	v_add_co_u32_e32 v18, vcc, s47, v6
	s_nop 1
	v_addc_co_u32_e32 v19, vcc, 0, v7, vcc
	v_add_co_u32_e32 v20, vcc, s49, v6
	s_nop 1
	v_addc_co_u32_e32 v21, vcc, 0, v7, vcc
	v_add_co_u32_e32 v22, vcc, s50, v6
	s_nop 1
	v_addc_co_u32_e32 v23, vcc, 0, v7, vcc
	global_load_dword v4, v[6:7], off
	global_load_dword v27, v[8:9], off
	global_load_dword v28, v[10:11], off
	global_load_dword v29, v[12:13], off
	global_load_dword v30, v[16:17], off
	global_load_dword v31, v[18:19], off
	global_load_dword v32, v[20:21], off
	global_load_dword v33, v[22:23], off
	v_add_co_u32_e32 v8, vcc, s51, v6
	s_nop 1
	v_addc_co_u32_e32 v9, vcc, 0, v7, vcc
	v_add_co_u32_e32 v10, vcc, s52, v6
	s_nop 1
	v_addc_co_u32_e32 v11, vcc, 0, v7, vcc
	v_add_co_u32_e32 v12, vcc, s53, v6
	s_nop 1
	v_addc_co_u32_e32 v13, vcc, 0, v7, vcc
	v_add_co_u32_e32 v16, vcc, s54, v6
	s_nop 1
	v_addc_co_u32_e32 v17, vcc, 0, v7, vcc
	v_add_co_u32_e32 v18, vcc, s55, v6
	s_nop 1
	v_addc_co_u32_e32 v19, vcc, 0, v7, vcc
	v_add_co_u32_e32 v20, vcc, s56, v6
	s_nop 1
	v_addc_co_u32_e32 v21, vcc, 0, v7, vcc
	v_add_co_u32_e32 v22, vcc, s57, v6
	s_nop 1
	v_addc_co_u32_e32 v23, vcc, 0, v7, vcc
	v_add_co_u32_e32 v6, vcc, s60, v6
	s_nop 1
	v_addc_co_u32_e32 v7, vcc, 0, v7, vcc
	global_load_dword v8, v[8:9], off
	s_nop 0
	global_load_dword v9, v[10:11], off
	s_nop 0
	global_load_dword v10, v[12:13], off
	global_load_dword v11, v[16:17], off
	s_nop 0
	global_load_dword v12, v[18:19], off
	global_load_dword v13, v[20:21], off
	global_load_dword v16, v[22:23], off
	s_nop 0
	global_load_dword v6, v[6:7], off
	v_mul_lo_u32 v7, v26, s39
	v_lshl_add_u32 v7, v25, 2, v7
	v_ashrrev_i32_e32 v21, 3, v24
	s_waitcnt vmcnt(15)
	ds_write_b32 v7, v4
	s_waitcnt vmcnt(14)
	ds_write_b32 v7, v27 offset:1040
	s_waitcnt vmcnt(13)
	ds_write_b32 v7, v28 offset:2080
	s_waitcnt vmcnt(12)
	ds_write_b32 v7, v29 offset:3120
	s_waitcnt vmcnt(11)
	ds_write_b32 v7, v30 offset:4160
	s_waitcnt vmcnt(10)
	ds_write_b32 v7, v31 offset:5200
	s_waitcnt vmcnt(9)
	ds_write_b32 v7, v32 offset:6240
	s_waitcnt vmcnt(8)
	ds_write_b32 v7, v33 offset:7280
	s_waitcnt vmcnt(7)
	ds_write_b32 v7, v8 offset:8320
	s_waitcnt vmcnt(6)
	ds_write_b32 v7, v9 offset:9360
	s_waitcnt vmcnt(5)
	ds_write_b32 v7, v10 offset:10400
	s_waitcnt vmcnt(4)
	ds_write_b32 v7, v11 offset:11440
	s_waitcnt vmcnt(3)
	ds_write_b32 v7, v12 offset:12480
	s_waitcnt vmcnt(2)
	ds_write_b32 v7, v13 offset:13520
	s_waitcnt vmcnt(1)
	ds_write_b32 v7, v16 offset:14560
	s_waitcnt vmcnt(0)
	ds_write_b32 v7, v6 offset:15600
	v_lshlrev_b32_e32 v4, 3, v24
	v_and_b32_e32 v6, 56, v4
	v_mul_u32_u24_e32 v20, 0x104, v6
	v_lshl_add_u32 v8, v21, 2, v20
	v_add_u32_e32 v9, 0x400, v8
	s_waitcnt lgkmcnt(0)
	s_barrier
	v_lshrrev_b32_e32 v4, 5, v6
	v_and_b32_e32 v18, 31, v6
	v_lshlrev_b32_e32 v4, 16, v4
	v_lshl_add_u32 v4, v18, 1, v4
	ds_read2_b32 v[6:7], v9 offset0:134 offset1:199
	ds_read2_b32 v[10:11], v9 offset0:4 offset1:69
	ds_read2_b32 v[12:13], v8 offset0:130 offset1:195
	ds_read2_b32 v[16:17], v8 offset1:65
	v_lshl_add_u64 v[18:19], s[16:17], 0, v[4:5]
	v_add_u32_e32 v4, 0x100, v24
	v_ashrrev_i32_e32 v4, 3, v4
	s_waitcnt lgkmcnt(2)
	v_cvt_pk_f16_f32 v8, v10, v11
	v_add_u32_e32 v10, s12, v21
	v_lshl_add_u32 v22, v4, 2, v20
	v_cvt_pk_f16_f32 v9, v6, v7
	s_waitcnt lgkmcnt(0)
	v_cvt_pk_f16_f32 v6, v16, v17
	v_ashrrev_i32_e32 v11, 31, v10
	v_add_u32_e32 v16, 0x400, v22
	v_cvt_pk_f16_f32 v7, v12, v13
	v_lshlrev_b64 v[10:11], 6, v[10:11]
	ds_read2_b32 v[12:13], v16 offset0:134 offset1:199
	ds_read2_b32 v[16:17], v16 offset0:4 offset1:69
	ds_read2_b32 v[20:21], v22 offset0:130 offset1:195
	ds_read2_b32 v[22:23], v22 offset1:65
	v_lshl_add_u64 v[10:11], v[18:19], 0, v[10:11]
	global_store_dwordx4 v[10:11], v[6:9], off
	v_add_u32_e32 v10, s12, v4
	v_ashrrev_i32_e32 v11, 31, v10
	v_lshlrev_b64 v[10:11], 6, v[10:11]
	s_waitcnt lgkmcnt(3)
	v_cvt_pk_f16_f32 v9, v12, v13
	s_waitcnt lgkmcnt(2)
	v_cvt_pk_f16_f32 v8, v16, v17
	s_waitcnt lgkmcnt(1)
	v_cvt_pk_f16_f32 v7, v20, v21
	s_waitcnt lgkmcnt(0)
	v_cvt_pk_f16_f32 v6, v22, v23
	v_lshl_add_u64 v[10:11], v[18:19], 0, v[10:11]
	global_store_dwordx4 v[10:11], v[6:9], off
	s_barrier

; template <int NI, class LA, class LB, class EP>
; __device__ __forceinline__ void gemm_tile(int K, LA loadA, LB loadB, EP epi, char* smem) {
;     ...
;   for (int kt = 0; kt < nk; ++kt) {
;     __syncthreads();
; #pragma unroll
;     for (int i = 0; i < 4; ++i) *(uint4*)&sA[(lr + 32 * i) * 72 + lc] = ra[i];
; #pragma unroll
;     for (int i = 0; i < NB; ++i) *(uint4*)&sB[(lr + 32 * i) * 72 + lc] = rb[i];
;     __syncthreads();
;     if (kt + 1 < nk) {
;       const int kk = (kt + 1) * 64 + lc;
; #pragma unroll
;       for (int i = 0; i < 4; ++i) ra[i] = loadA(lr + 32 * i, kk);
; #pragma unroll
;       for (int i = 0; i < NB; ++i) rb[i] = loadB(lr + 32 * i, kk);
;     }
; #pragma unroll
;     for (int s = 0; s < 4; ++s) {
;       h8 af[2], bf[NI];
; #pragma unroll
;       for (int mi = 0; mi < 2; ++mi)
;         af[mi] = *(const h8*)&sA[(wm * 64 + mi * 32 + (lane & 31)) * 72 + s * 16 + (lane >> 5) * 8];
; #pragma unroll
;       for (int ni = 0; ni < NI; ++ni)
;         bf[ni] = *(const h8*)&sB[(wn * (NI * 32) + ni * 32 + (lane & 31)) * 72 + s * 16 + (lane >> 5) * 8];
; #pragma unroll
;       for (int mi = 0; mi < 2; ++mi)
; #pragma unroll
;         for (int ni = 0; ni < NI; ++ni)
;           acc[mi][ni] = __builtin_amdgcn_mfma_f32_32x32x16_f16(af[mi], bf[ni], acc[mi][ni], 0, 0, 0);
;     }
.LBB0_1743:
	s_waitcnt vmcnt(63) expcnt(7) lgkmcnt(15)
	s_barrier
	s_waitcnt vmcnt(7)
	ds_write_b128 v172, v[66:69]
	s_waitcnt vmcnt(6)
	ds_write_b128 v172, v[70:73] offset:4608
	s_waitcnt vmcnt(5)
	ds_write_b128 v172, v[94:97] offset:9216
	s_waitcnt vmcnt(4)
	ds_write_b128 v172, v[78:81] offset:13824
	s_waitcnt vmcnt(3)
	ds_write_b128 v172, v[90:93] offset:18432
	s_waitcnt vmcnt(2)
	ds_write_b128 v172, v[74:77] offset:23040
	s_waitcnt vmcnt(1)
	ds_write_b128 v172, v[86:89] offset:27648
	s_waitcnt vmcnt(0)
	ds_write_b128 v172, v[82:85] offset:32256
	s_waitcnt lgkmcnt(0)
	s_barrier
	ds_read_b128 v[66:69], v162
	ds_read_b128 v[70:73], v163 offset:18432
	ds_read_b128 v[74:77], v162 offset:32
	ds_read_b128 v[78:81], v163 offset:18464
	ds_read_b128 v[82:85], v171 offset:18432
	ds_read_b128 v[174:177], v163 offset:23136
	s_waitcnt lgkmcnt(4)
	v_mfma_f32_32x32x16_f16 v[50:65], v[66:69], v[70:73], v[50:65]
	s_mov_b32 s2, 0x15680000
	s_waitcnt lgkmcnt(1)
	v_mfma_f32_32x32x16_f16 v[34:49], v[66:69], v[82:85], v[34:49]
	ds_read_b128 v[66:69], v162 offset:4608
	ds_read_b128 v[86:89], v162 offset:4640
	s_waitcnt lgkmcnt(1)
	v_mfma_f32_32x32x16_f16 v[18:33], v[66:69], v[70:73], v[18:33]
	v_mfma_f32_32x32x16_f16 v[2:17], v[66:69], v[82:85], v[2:17]
	ds_read_b128 v[66:69], v163 offset:23072
	ds_read_b128 v[70:73], v163 offset:23104
	v_mfma_f32_32x32x16_f16 v[50:65], v[74:77], v[78:81], v[50:65]
	s_waitcnt lgkmcnt(1)
	v_mfma_f32_32x32x16_f16 v[34:49], v[74:77], v[66:69], v[34:49]
	v_mfma_f32_32x32x16_f16 v[18:33], v[86:89], v[78:81], v[18:33]
	v_mfma_f32_32x32x16_f16 v[2:17], v[86:89], v[66:69], v[2:17]
	ds_read_b128 v[66:69], v162 offset:64
	ds_read_b128 v[74:77], v163 offset:18496
	ds_read_b128 v[78:81], v162 offset:96
	ds_read_b128 v[82:85], v163 offset:18528
	ds_read_b128 v[86:89], v162 offset:4672
	ds_read_b128 v[178:181], v162 offset:4704
	s_waitcnt lgkmcnt(4)
	v_mfma_f32_32x32x16_f16 v[50:65], v[66:69], v[74:77], v[50:65]
	v_mfma_f32_32x32x16_f16 v[34:49], v[66:69], v[70:73], v[34:49]
	v_lshl_add_u64 v[66:67], v[166:167], 0, s[40:41]
	v_add_co_u32_e32 v90, vcc, s73, v66
	v_lshl_add_u64 v[68:69], v[164:165], 0, s[40:41]
	s_nop 0
	v_addc_co_u32_e32 v91, vcc, 0, v67, vcc
	s_add_u32 s40, s40, 0x80
	s_waitcnt lgkmcnt(1)
	v_mfma_f32_32x32x16_f16 v[18:33], v[86:89], v[74:77], v[18:33]
	v_add_co_u32_e32 v74, vcc, s72, v66
	s_addc_u32 s41, s41, 0
	s_nop 0
	v_addc_co_u32_e32 v75, vcc, 0, v67, vcc
	v_add_co_u32_e32 v76, vcc, s77, v66
	v_mfma_f32_32x32x16_f16 v[2:17], v[86:89], v[70:73], v[2:17]
	s_nop 0
	v_addc_co_u32_e32 v77, vcc, 0, v67, vcc
	v_add_co_u32_e32 v86, vcc, s2, v68
	s_mov_b32 s2, 0x15688000
	s_nop 0
	v_addc_co_u32_e32 v87, vcc, 0, v69, vcc
	v_add_co_u32_e32 v88, vcc, s2, v68
	s_mov_b32 s2, 0x15690000
	s_nop 0
	v_addc_co_u32_e32 v89, vcc, 0, v69, vcc
	v_add_co_u32_e32 v188, vcc, s2, v68
	s_mov_b32 s2, 0x15698000
	s_nop 0
	v_addc_co_u32_e32 v189, vcc, 0, v69, vcc
	v_add_co_u32_e32 v190, vcc, s2, v68
	v_mfma_f32_32x32x16_f16 v[50:65], v[78:81], v[82:85], v[50:65]
	s_nop 0
	v_addc_co_u32_e32 v191, vcc, 0, v69, vcc
	s_cmpk_lg_i32 s40, 0x380
	v_mfma_f32_32x32x16_f16 v[34:49], v[78:81], v[174:177], v[34:49]
	global_load_dwordx4 v[66:69], v[66:67], off offset:128
	s_nop 0
	global_load_dwordx4 v[70:73], v[90:91], off offset:128
	global_load_dwordx4 v[94:97], v[74:75], off offset:128
	global_load_dwordx4 v[78:81], v[76:77], off offset:128
	s_nop 0
	global_load_dwordx4 v[90:93], v[86:87], off offset:128
	global_load_dwordx4 v[74:77], v[88:89], off offset:128
	s_nop 0
	global_load_dwordx4 v[86:89], v[188:189], off offset:128
	s_waitcnt lgkmcnt(0)
	v_mfma_f32_32x32x16_f16 v[18:33], v[178:181], v[82:85], v[18:33]
	global_load_dwordx4 v[82:85], v[190:191], off offset:128
	v_mfma_f32_32x32x16_f16 v[2:17], v[178:181], v[174:177], v[2:17]
	s_cbranch_scc1 .LBB0_1743
	s_barrier
	s_waitcnt vmcnt(7)
	ds_write_b128 v172, v[66:69]
	s_waitcnt vmcnt(6)
	ds_write_b128 v172, v[70:73] offset:4608
	s_waitcnt vmcnt(5)
	ds_write_b128 v172, v[94:97] offset:9216
	s_waitcnt vmcnt(4)
	ds_write_b128 v172, v[78:81] offset:13824
	s_waitcnt vmcnt(3)
	ds_write_b128 v172, v[90:93] offset:18432
	s_waitcnt vmcnt(2)
	ds_write_b128 v172, v[74:77] offset:23040
	s_waitcnt vmcnt(1)
	ds_write_b128 v172, v[86:89] offset:27648
	s_waitcnt vmcnt(0)
	ds_write_b128 v172, v[82:85] offset:32256
	s_waitcnt lgkmcnt(0)
	s_barrier
; __device__ __forceinline__ float sigmoidf_(float x) { return 1.f / (1.f + __expf(-x)); }
; template <int NI, class LA, class LB, class EP>
; __device__ __forceinline__ void gemm_tile(int K, LA loadA, LB loadB, EP epi, char* smem) {
;     ...
; #pragma unroll
;     for (int s = 0; s < 4; ++s) {
;       h8 af[2], bf[NI];
; #pragma unroll
;       for (int mi = 0; mi < 2; ++mi)
;         af[mi] = *(const h8*)&sA[(wm * 64 + mi * 32 + (lane & 31)) * 72 + s * 16 + (lane >> 5) * 8];
; #pragma unroll
;       for (int ni = 0; ni < NI; ++ni)
;         bf[ni] = *(const h8*)&sB[(wn * (NI * 32) + ni * 32 + (lane & 31)) * 72 + s * 16 + (lane >> 5) * 8];
; #pragma unroll
;       for (int mi = 0; mi < 2; ++mi)
; #pragma unroll
;         for (int ni = 0; ni < NI; ++ni)
;           acc[mi][ni] = __builtin_amdgcn_mfma_f32_32x32x16_f16(af[mi], bf[ni], acc[mi][ni], 0, 0, 0);
;     }
; __device__ __forceinline__ void phase_merge(const KP& p, char* smem, int* q, int xcc) {
;     ...
;           [&](int mi, int ni, int r, int row, int col, float v) {
;             const float gz = (float)G[(size_t)row * NU + col];
;             tot[mi][ni][r] += sigmoidf_(gz) * v;
;           },
	ds_read_b128 v[66:69], v162 offset:4608
	ds_read_b128 v[70:73], v171 offset:18432
	ds_read_b128 v[74:77], v162
	ds_read_b128 v[78:81], v162 offset:32
	ds_read_b128 v[82:85], v163 offset:18432
	ds_read_b128 v[86:89], v163 offset:18464
	s_waitcnt lgkmcnt(1)
	v_mfma_f32_32x32x16_f16 v[50:65], v[74:77], v[82:85], v[50:65]
	s_lshl_b32 s2, s56, 11
	s_add_u32 s2, s52, s2
	s_addc_u32 s3, s53, 0
	v_lshlrev_b32_e32 v0, 1, v0
	s_add_i32 s56, s56, 1
	s_add_u32 s38, s38, 0x100000
	s_addc_u32 s39, s39, 0
	v_mfma_f32_32x32x16_f16 v[34:49], v[74:77], v[70:73], v[34:49]
	s_cmp_lg_u32 s56, 3
	v_mfma_f32_32x32x16_f16 v[18:33], v[66:69], v[82:85], v[18:33]
	v_mfma_f32_32x32x16_f16 v[2:17], v[66:69], v[70:73], v[2:17]
	ds_read_b128 v[66:69], v162 offset:4640
	ds_read_b128 v[70:73], v163 offset:23072
	s_waitcnt lgkmcnt(2)
	v_mfma_f32_32x32x16_f16 v[50:65], v[78:81], v[86:89], v[50:65]
	s_waitcnt lgkmcnt(0)
	v_mfma_f32_32x32x16_f16 v[34:49], v[78:81], v[70:73], v[34:49]
	v_mfma_f32_32x32x16_f16 v[18:33], v[66:69], v[86:89], v[18:33]
	v_mfma_f32_32x32x16_f16 v[2:17], v[66:69], v[70:73], v[2:17]
	ds_read_b128 v[66:69], v162 offset:64
	ds_read_b128 v[70:73], v162 offset:4672
	ds_read_b128 v[74:77], v163 offset:18496
	ds_read_b128 v[78:81], v163 offset:23104
	s_waitcnt lgkmcnt(1)
	v_mfma_f32_32x32x16_f16 v[50:65], v[66:69], v[74:77], v[50:65]
	s_waitcnt lgkmcnt(0)
	v_mfma_f32_32x32x16_f16 v[34:49], v[66:69], v[78:81], v[34:49]
	v_mfma_f32_32x32x16_f16 v[18:33], v[70:73], v[74:77], v[18:33]
	v_mfma_f32_32x32x16_f16 v[2:17], v[70:73], v[78:81], v[2:17]
	ds_read_b128 v[66:69], v162 offset:96
	ds_read_b128 v[70:73], v162 offset:4704
	ds_read_b128 v[74:77], v163 offset:18528
	ds_read_b128 v[78:81], v163 offset:23136
	s_waitcnt lgkmcnt(1)
	v_mfma_f32_32x32x16_f16 v[50:65], v[66:69], v[74:77], v[50:65]
	s_waitcnt lgkmcnt(0)
	v_mfma_f32_32x32x16_f16 v[34:49], v[66:69], v[78:81], v[34:49]
	v_mfma_f32_32x32x16_f16 v[18:33], v[70:73], v[74:77], v[18:33]
	v_mfma_f32_32x32x16_f16 v[2:17], v[70:73], v[78:81], v[2:17]
	v_lshrrev_b32_e32 v94, 7, v224
	v_lshlrev_b32_e32 v94, 4, v94
	v_bfe_u32 v95, v224, 5, 1
	v_add_u32_e32 v94, v94, v95
	v_mul_u32_u24_e32 v94, 0xe800, v94
	v_bfe_u32 v95, v224, 6, 1
	v_lshl_add_u32 v94, v95, 7, v94
	v_and_b32_e32 v95, 31, v224
	v_lshl_add_u32 v94, v95, 1, v94
	s_mov_b64 s[40:41], s[2:3]
	v_mov_b32_e32 v96, v94
	global_load_ushort v192, v96, s[40:41]
	v_add_u32_e32 v96, 0x3a00, v94
	global_load_ushort v193, v96, s[40:41]
	v_add_u32_e32 v96, 0x7400, v94
	global_load_ushort v194, v96, s[40:41]
	v_add_u32_e32 v96, 0xae00, v94
	global_load_ushort v195, v96, s[40:41]
	v_add_u32_e32 v96, 0x1d000, v94
	global_load_ushort v196, v96, s[40:41]
	v_add_u32_e32 v96, 0x20a00, v94
	global_load_ushort v197, v96, s[40:41]
	v_add_u32_e32 v96, 0x24400, v94
	global_load_ushort v198, v96, s[40:41]
	v_add_u32_e32 v96, 0x27e00, v94
	global_load_ushort v199, v96, s[40:41]
	v_add_u32_e32 v96, 0x3a000, v94
	global_load_ushort v200, v96, s[40:41]
	v_add_u32_e32 v96, 0x3da00, v94
	global_load_ushort v201, v96, s[40:41]
	v_add_u32_e32 v96, 0x41400, v94
	global_load_ushort v202, v96, s[40:41]
	v_add_u32_e32 v96, 0x44e00, v94
	global_load_ushort v203, v96, s[40:41]
	v_add_u32_e32 v96, 0x57000, v94
	global_load_ushort v204, v96, s[40:41]
	v_add_u32_e32 v96, 0x5aa00, v94
	global_load_ushort v205, v96, s[40:41]
	v_add_u32_e32 v96, 0x5e400, v94
	global_load_ushort v206, v96, s[40:41]
	v_add_u32_e32 v96, 0x61e00, v94
	global_load_ushort v207, v96, s[40:41]
	v_mov_b32_e32 v96, v94
	global_load_ushort v208, v96, s[40:41] offset:64
	v_add_u32_e32 v96, 0x3a00, v94
	global_load_ushort v209, v96, s[40:41] offset:64
	v_add_u32_e32 v96, 0x7400, v94
	global_load_ushort v210, v96, s[40:41] offset:64
	v_add_u32_e32 v96, 0xae00, v94
	global_load_ushort v211, v96, s[40:41] offset:64
	v_add_u32_e32 v96, 0x1d000, v94
	global_load_ushort v212, v96, s[40:41] offset:64
	v_add_u32_e32 v96, 0x20a00, v94
	global_load_ushort v213, v96, s[40:41] offset:64
	v_add_u32_e32 v96, 0x24400, v94
	global_load_ushort v214, v96, s[40:41] offset:64
	v_add_u32_e32 v96, 0x27e00, v94
	global_load_ushort v215, v96, s[40:41] offset:64
	v_add_u32_e32 v96, 0x3a000, v94
	global_load_ushort v216, v96, s[40:41] offset:64
	v_add_u32_e32 v96, 0x3da00, v94
	global_load_ushort v217, v96, s[40:41] offset:64
	v_add_u32_e32 v96, 0x41400, v94
	global_load_ushort v218, v96, s[40:41] offset:64
	v_add_u32_e32 v96, 0x44e00, v94
	global_load_ushort v219, v96, s[40:41] offset:64
	v_add_u32_e32 v96, 0x57000, v94
	global_load_ushort v220, v96, s[40:41] offset:64
	v_add_u32_e32 v96, 0x5aa00, v94
	global_load_ushort v221, v96, s[40:41] offset:64
	v_add_u32_e32 v96, 0x5e400, v94
	global_load_ushort v222, v96, s[40:41] offset:64
	v_add_u32_e32 v96, 0x61e00, v94
	global_load_ushort v223, v96, s[40:41] offset:64
	s_nop 7
	s_waitcnt vmcnt(30)
	v_cvt_f32_f16_e32 v68, v192
	v_cvt_f32_f16_e32 v69, v193
	v_add_u32_e32 v96, 0x74000, v94
	global_load_ushort v192, v96, s[40:41]
	v_add_u32_e32 v96, 0x77a00, v94
	global_load_ushort v193, v96, s[40:41]
	v_mul_f32_e32 v68, 0xbfb8aa3b, v68
	v_mul_f32_e32 v69, 0xbfb8aa3b, v69
	v_exp_f32_e32 v68, v68
	v_exp_f32_e32 v69, v69
	s_nop 0
	v_pk_add_f32 v[68:69], v[68:69], 1.0 op_sel_hi:[1,0]
	s_nop 0
	v_div_scale_f32 v70, s[2:3], v69, v69, 1.0
	v_rcp_f32_e32 v71, v70
	s_nop 0
	v_fma_f32 v72, -v70, v71, 1.0
	v_fmac_f32_e32 v71, v72, v71
	v_div_scale_f32 v72, vcc, 1.0, v69, 1.0
	v_mul_f32_e32 v73, v72, v71
	v_fma_f32 v74, -v70, v73, v72
	v_fmac_f32_e32 v73, v74, v71
	v_fma_f32 v70, -v70, v73, v72
	v_div_fmas_f32 v70, v70, v71, v73
	v_div_fixup_f32 v69, v70, v69, 1.0
	v_div_scale_f32 v70, s[2:3], v68, v68, 1.0
	v_rcp_f32_e32 v71, v70
	s_nop 0
	v_fma_f32 v72, -v70, v71, 1.0
	v_fmac_f32_e32 v71, v72, v71
	v_div_scale_f32 v72, vcc, 1.0, v68, 1.0
	v_mul_f32_e32 v73, v72, v71
	v_fma_f32 v74, -v70, v73, v72
	v_fmac_f32_e32 v73, v74, v71
	v_fma_f32 v70, -v70, v73, v72
	v_div_fmas_f32 v70, v70, v71, v73
	v_div_fixup_f32 v68, v70, v68, 1.0
	v_pk_fma_f32 v[160:161], v[50:51], v[68:69], v[160:161]
	s_waitcnt vmcnt(30)
; __device__ __forceinline__ float sigmoidf_(float x) { return 1.f / (1.f + __expf(-x)); }
; __device__ __forceinline__ void phase_merge(const KP& p, char* smem, int* q, int xcc) {
;     ...
;           [&](int mi, int ni, int r, int row, int col, float v) {
;             const float gz = (float)G[(size_t)row * NU + col];
;             tot[mi][ni][r] += sigmoidf_(gz) * v;
;           },
	v_cvt_f32_f16_e32 v68, v194
	v_cvt_f32_f16_e32 v69, v195
	v_add_u32_e32 v96, 0x7b400, v94
	global_load_ushort v194, v96, s[40:41]
	v_add_u32_e32 v96, 0x7ee00, v94
	global_load_ushort v195, v96, s[40:41]
	v_mul_f32_e32 v68, 0xbfb8aa3b, v68
	v_mul_f32_e32 v69, 0xbfb8aa3b, v69
	v_exp_f32_e32 v68, v68
	v_exp_f32_e32 v69, v69
	s_nop 0
	v_pk_add_f32 v[68:69], v[68:69], 1.0 op_sel_hi:[1,0]
	s_nop 0
	v_div_scale_f32 v70, s[2:3], v69, v69, 1.0
	v_rcp_f32_e32 v71, v70
	s_nop 0
	v_fma_f32 v72, -v70, v71, 1.0
	v_fmac_f32_e32 v71, v72, v71
	v_div_scale_f32 v72, vcc, 1.0, v69, 1.0
	v_mul_f32_e32 v73, v72, v71
	v_fma_f32 v74, -v70, v73, v72
	v_fmac_f32_e32 v73, v74, v71
	v_fma_f32 v70, -v70, v73, v72
	v_div_fmas_f32 v70, v70, v71, v73
	v_div_fixup_f32 v69, v70, v69, 1.0
	v_div_scale_f32 v70, s[2:3], v68, v68, 1.0
	v_rcp_f32_e32 v71, v70
	s_nop 0
	v_fma_f32 v72, -v70, v71, 1.0
	v_fmac_f32_e32 v71, v72, v71
	v_div_scale_f32 v72, vcc, 1.0, v68, 1.0
	v_mul_f32_e32 v73, v72, v71
	v_fma_f32 v74, -v70, v73, v72
	v_fmac_f32_e32 v73, v74, v71
	v_fma_f32 v70, -v70, v73, v72
	v_div_fmas_f32 v70, v70, v71, v73
	v_div_fixup_f32 v68, v70, v68, 1.0
	v_pk_fma_f32 v[158:159], v[52:53], v[68:69], v[158:159]
	s_waitcnt vmcnt(30)
	v_cvt_f32_f16_e32 v68, v196
	v_cvt_f32_f16_e32 v69, v197
	v_add_u32_e32 v96, 0x91000, v94
	global_load_ushort v196, v96, s[40:41]
	v_add_u32_e32 v96, 0x94a00, v94
	global_load_ushort v197, v96, s[40:41]
	v_mul_f32_e32 v68, 0xbfb8aa3b, v68
	v_mul_f32_e32 v69, 0xbfb8aa3b, v69
	v_exp_f32_e32 v68, v68
	v_exp_f32_e32 v69, v69
	s_nop 0
	v_pk_add_f32 v[68:69], v[68:69], 1.0 op_sel_hi:[1,0]
	s_nop 0
	v_div_scale_f32 v70, s[2:3], v69, v69, 1.0
	v_rcp_f32_e32 v71, v70
	s_nop 0
	v_fma_f32 v72, -v70, v71, 1.0
	v_fmac_f32_e32 v71, v72, v71
	v_div_scale_f32 v72, vcc, 1.0, v69, 1.0
	v_mul_f32_e32 v73, v72, v71
	v_fma_f32 v74, -v70, v73, v72
	v_fmac_f32_e32 v73, v74, v71
	v_fma_f32 v70, -v70, v73, v72
	v_div_fmas_f32 v70, v70, v71, v73
	v_div_fixup_f32 v69, v70, v69, 1.0
	v_div_scale_f32 v70, s[2:3], v68, v68, 1.0
	v_rcp_f32_e32 v71, v70
	s_nop 0
	v_fma_f32 v72, -v70, v71, 1.0
	v_fmac_f32_e32 v71, v72, v71
	v_div_scale_f32 v72, vcc, 1.0, v68, 1.0
	v_mul_f32_e32 v73, v72, v71
	v_fma_f32 v74, -v70, v73, v72
	v_fmac_f32_e32 v73, v74, v71
	v_fma_f32 v70, -v70, v73, v72
	v_div_fmas_f32 v70, v70, v71, v73
	v_div_fixup_f32 v68, v70, v68, 1.0
	v_pk_fma_f32 v[156:157], v[54:55], v[68:69], v[156:157]
	s_waitcnt vmcnt(30)
	v_cvt_f32_f16_e32 v68, v198
	v_cvt_f32_f16_e32 v69, v199
	v_add_u32_e32 v96, 0x98400, v94
	global_load_ushort v198, v96, s[40:41]
	v_add_u32_e32 v96, 0x9be00, v94
	global_load_ushort v199, v96, s[40:41]
	v_mul_f32_e32 v68, 0xbfb8aa3b, v68
	v_mul_f32_e32 v69, 0xbfb8aa3b, v69
	v_exp_f32_e32 v68, v68
	v_exp_f32_e32 v69, v69
	s_nop 0
	v_pk_add_f32 v[68:69], v[68:69], 1.0 op_sel_hi:[1,0]
	s_nop 0
	v_div_scale_f32 v70, s[2:3], v69, v69, 1.0
	v_rcp_f32_e32 v71, v70
	s_nop 0
	v_fma_f32 v72, -v70, v71, 1.0
	v_fmac_f32_e32 v71, v72, v71
	v_div_scale_f32 v72, vcc, 1.0, v69, 1.0
	v_mul_f32_e32 v73, v72, v71
	v_fma_f32 v74, -v70, v73, v72
	v_fmac_f32_e32 v73, v74, v71
	v_fma_f32 v70, -v70, v73, v72
	v_div_fmas_f32 v70, v70, v71, v73
	v_div_fixup_f32 v69, v70, v69, 1.0
	v_div_scale_f32 v70, s[2:3], v68, v68, 1.0
	v_rcp_f32_e32 v71, v70
	s_nop 0
	v_fma_f32 v72, -v70, v71, 1.0
	v_fmac_f32_e32 v71, v72, v71
	v_div_scale_f32 v72, vcc, 1.0, v68, 1.0
	v_mul_f32_e32 v73, v72, v71
	v_fma_f32 v74, -v70, v73, v72
	v_fmac_f32_e32 v73, v74, v71
	v_fma_f32 v70, -v70, v73, v72
	v_div_fmas_f32 v70, v70, v71, v73
	v_div_fixup_f32 v68, v70, v68, 1.0
	v_pk_fma_f32 v[154:155], v[56:57], v[68:69], v[154:155]
	s_waitcnt vmcnt(30)
	v_cvt_f32_f16_e32 v68, v200
	v_cvt_f32_f16_e32 v69, v201
	v_add_u32_e32 v96, 0xae000, v94
	global_load_ushort v200, v96, s[40:41]
	v_add_u32_e32 v96, 0xb1a00, v94
	global_load_ushort v201, v96, s[40:41]
	v_mul_f32_e32 v68, 0xbfb8aa3b, v68
	v_mul_f32_e32 v69, 0xbfb8aa3b, v69
	v_exp_f32_e32 v68, v68
	v_exp_f32_e32 v69, v69
	s_nop 0
	v_pk_add_f32 v[68:69], v[68:69], 1.0 op_sel_hi:[1,0]
	s_nop 0
	v_div_scale_f32 v70, s[2:3], v69, v69, 1.0
	v_rcp_f32_e32 v71, v70
	s_nop 0
	v_fma_f32 v72, -v70, v71, 1.0
	v_fmac_f32_e32 v71, v72, v71
	v_div_scale_f32 v72, vcc, 1.0, v69, 1.0
	v_mul_f32_e32 v73, v72, v71
	v_fma_f32 v74, -v70, v73, v72
	v_fmac_f32_e32 v73, v74, v71
	v_fma_f32 v70, -v70, v73, v72
	v_div_fmas_f32 v70, v70, v71, v73
	v_div_fixup_f32 v69, v70, v69, 1.0
	v_div_scale_f32 v70, s[2:3], v68, v68, 1.0
	v_rcp_f32_e32 v71, v70
	s_nop 0
	v_fma_f32 v72, -v70, v71, 1.0
	v_fmac_f32_e32 v71, v72, v71
	v_div_scale_f32 v72, vcc, 1.0, v68, 1.0
	v_mul_f32_e32 v73, v72, v71
	v_fma_f32 v74, -v70, v73, v72
	v_fmac_f32_e32 v73, v74, v71
	v_fma_f32 v70, -v70, v73, v72
	v_div_fmas_f32 v70, v70, v71, v73
	v_div_fixup_f32 v68, v70, v68, 1.0
	v_pk_fma_f32 v[152:153], v[58:59], v[68:69], v[152:153]
	s_waitcnt vmcnt(30)
	v_cvt_f32_f16_e32 v68, v202
	v_cvt_f32_f16_e32 v69, v203
	v_add_u32_e32 v96, 0xb5400, v94
	global_load_ushort v202, v96, s[40:41]
	v_add_u32_e32 v96, 0xb8e00, v94
	global_load_ushort v203, v96, s[40:41]
	v_mul_f32_e32 v68, 0xbfb8aa3b, v68
	v_mul_f32_e32 v69, 0xbfb8aa3b, v69
	v_exp_f32_e32 v68, v68
	v_exp_f32_e32 v69, v69
	s_nop 0
	v_pk_add_f32 v[68:69], v[68:69], 1.0 op_sel_hi:[1,0]
	s_nop 0
	v_div_scale_f32 v70, s[2:3], v69, v69, 1.0
	v_rcp_f32_e32 v71, v70
	s_nop 0
	v_fma_f32 v72, -v70, v71, 1.0
	v_fmac_f32_e32 v71, v72, v71
	v_div_scale_f32 v72, vcc, 1.0, v69, 1.0
	v_mul_f32_e32 v73, v72, v71
	v_fma_f32 v74, -v70, v73, v72
	v_fmac_f32_e32 v73, v74, v71
	v_fma_f32 v70, -v70, v73, v72
	v_div_fmas_f32 v70, v70, v71, v73
	v_div_fixup_f32 v69, v70, v69, 1.0
	v_div_scale_f32 v70, s[2:3], v68, v68, 1.0
	v_rcp_f32_e32 v71, v70
	s_nop 0
	v_fma_f32 v72, -v70, v71, 1.0
	v_fmac_f32_e32 v71, v72, v71
	v_div_scale_f32 v72, vcc, 1.0, v68, 1.0
	v_mul_f32_e32 v73, v72, v71
	v_fma_f32 v74, -v70, v73, v72
	v_fmac_f32_e32 v73, v74, v71
	v_fma_f32 v70, -v70, v73, v72
	v_div_fmas_f32 v70, v70, v71, v73
	v_div_fixup_f32 v68, v70, v68, 1.0
	v_pk_fma_f32 v[150:151], v[60:61], v[68:69], v[150:151]
	s_waitcnt vmcnt(30)
; __device__ __forceinline__ float sigmoidf_(float x) { return 1.f / (1.f + __expf(-x)); }
; __device__ __forceinline__ void phase_merge(const KP& p, char* smem, int* q, int xcc) {
;     ...
;           [&](int mi, int ni, int r, int row, int col, float v) {
;             const float gz = (float)G[(size_t)row * NU + col];
;             tot[mi][ni][r] += sigmoidf_(gz) * v;
;           },
	v_cvt_f32_f16_e32 v68, v204
	v_cvt_f32_f16_e32 v69, v205
	v_add_u32_e32 v96, 0xcb000, v94
	global_load_ushort v204, v96, s[40:41]
	v_add_u32_e32 v96, 0xcea00, v94
	global_load_ushort v205, v96, s[40:41]
	v_mul_f32_e32 v68, 0xbfb8aa3b, v68
	v_mul_f32_e32 v69, 0xbfb8aa3b, v69
	v_exp_f32_e32 v68, v68
	v_exp_f32_e32 v69, v69
	s_nop 0
	v_pk_add_f32 v[68:69], v[68:69], 1.0 op_sel_hi:[1,0]
	s_nop 0
	v_div_scale_f32 v70, s[2:3], v69, v69, 1.0
	v_rcp_f32_e32 v71, v70
	s_nop 0
	v_fma_f32 v72, -v70, v71, 1.0
	v_fmac_f32_e32 v71, v72, v71
	v_div_scale_f32 v72, vcc, 1.0, v69, 1.0
	v_mul_f32_e32 v73, v72, v71
	v_fma_f32 v74, -v70, v73, v72
	v_fmac_f32_e32 v73, v74, v71
	v_fma_f32 v70, -v70, v73, v72
	v_div_fmas_f32 v70, v70, v71, v73
	v_div_fixup_f32 v69, v70, v69, 1.0
	v_div_scale_f32 v70, s[2:3], v68, v68, 1.0
	v_rcp_f32_e32 v71, v70
	s_nop 0
	v_fma_f32 v72, -v70, v71, 1.0
	v_fmac_f32_e32 v71, v72, v71
	v_div_scale_f32 v72, vcc, 1.0, v68, 1.0
	v_mul_f32_e32 v73, v72, v71
	v_fma_f32 v74, -v70, v73, v72
	v_fmac_f32_e32 v73, v74, v71
	v_fma_f32 v70, -v70, v73, v72
	v_div_fmas_f32 v70, v70, v71, v73
	v_div_fixup_f32 v68, v70, v68, 1.0
	v_pk_fma_f32 v[148:149], v[62:63], v[68:69], v[148:149]
	s_waitcnt vmcnt(30)
	v_cvt_f32_f16_e32 v68, v206
	v_cvt_f32_f16_e32 v69, v207
	v_add_u32_e32 v96, 0xd2400, v94
	global_load_ushort v206, v96, s[40:41]
	v_add_u32_e32 v96, 0xd5e00, v94
	global_load_ushort v207, v96, s[40:41]
	v_mul_f32_e32 v68, 0xbfb8aa3b, v68
	v_mul_f32_e32 v69, 0xbfb8aa3b, v69
	v_exp_f32_e32 v68, v68
	v_exp_f32_e32 v69, v69
	s_nop 0
	v_pk_add_f32 v[68:69], v[68:69], 1.0 op_sel_hi:[1,0]
	s_nop 0
	v_div_scale_f32 v70, s[2:3], v69, v69, 1.0
	v_rcp_f32_e32 v71, v70
	s_nop 0
	v_fma_f32 v72, -v70, v71, 1.0
	v_fmac_f32_e32 v71, v72, v71
	v_div_scale_f32 v72, vcc, 1.0, v69, 1.0
	v_mul_f32_e32 v73, v72, v71
	v_fma_f32 v74, -v70, v73, v72
	v_fmac_f32_e32 v73, v74, v71
	v_fma_f32 v70, -v70, v73, v72
	v_div_fmas_f32 v70, v70, v71, v73
	v_div_fixup_f32 v69, v70, v69, 1.0
	v_div_scale_f32 v70, s[2:3], v68, v68, 1.0
	v_rcp_f32_e32 v71, v70
	s_nop 0
	v_fma_f32 v72, -v70, v71, 1.0
	v_fmac_f32_e32 v71, v72, v71
	v_div_scale_f32 v72, vcc, 1.0, v68, 1.0
	v_mul_f32_e32 v73, v72, v71
	v_fma_f32 v74, -v70, v73, v72
	v_fmac_f32_e32 v73, v74, v71
	v_fma_f32 v70, -v70, v73, v72
	v_div_fmas_f32 v70, v70, v71, v73
	v_div_fixup_f32 v68, v70, v68, 1.0
	v_pk_fma_f32 v[146:147], v[64:65], v[68:69], v[146:147]
	s_waitcnt vmcnt(30)
	v_cvt_f32_f16_e32 v68, v208
	v_cvt_f32_f16_e32 v69, v209
	v_add_u32_e32 v96, 0x74000, v94
	global_load_ushort v208, v96, s[40:41] offset:64
	v_add_u32_e32 v96, 0x77a00, v94
	global_load_ushort v209, v96, s[40:41] offset:64
	v_mul_f32_e32 v68, 0xbfb8aa3b, v68
	v_mul_f32_e32 v69, 0xbfb8aa3b, v69
	v_exp_f32_e32 v68, v68
	v_exp_f32_e32 v69, v69
	s_nop 0
	v_pk_add_f32 v[68:69], v[68:69], 1.0 op_sel_hi:[1,0]
	s_nop 0
	v_div_scale_f32 v70, s[2:3], v69, v69, 1.0
	v_rcp_f32_e32 v71, v70
	s_nop 0
	v_fma_f32 v72, -v70, v71, 1.0
	v_fmac_f32_e32 v71, v72, v71
	v_div_scale_f32 v72, vcc, 1.0, v69, 1.0
	v_mul_f32_e32 v73, v72, v71
	v_fma_f32 v74, -v70, v73, v72
	v_fmac_f32_e32 v73, v74, v71
	v_fma_f32 v70, -v70, v73, v72
	v_div_fmas_f32 v70, v70, v71, v73
	v_div_fixup_f32 v69, v70, v69, 1.0
	v_div_scale_f32 v70, s[2:3], v68, v68, 1.0
	v_rcp_f32_e32 v71, v70
	s_nop 0
	v_fma_f32 v72, -v70, v71, 1.0
	v_fmac_f32_e32 v71, v72, v71
	v_div_scale_f32 v72, vcc, 1.0, v68, 1.0
	v_mul_f32_e32 v73, v72, v71
	v_fma_f32 v74, -v70, v73, v72
	v_fmac_f32_e32 v73, v74, v71
	v_fma_f32 v70, -v70, v73, v72
	v_div_fmas_f32 v70, v70, v71, v73
	v_div_fixup_f32 v68, v70, v68, 1.0
	v_pk_fma_f32 v[144:145], v[34:35], v[68:69], v[144:145]
	s_waitcnt vmcnt(30)
	v_cvt_f32_f16_e32 v68, v210
	v_cvt_f32_f16_e32 v69, v211
	v_add_u32_e32 v96, 0x7b400, v94
	global_load_ushort v210, v96, s[40:41] offset:64
	v_add_u32_e32 v96, 0x7ee00, v94
	global_load_ushort v211, v96, s[40:41] offset:64
	v_mul_f32_e32 v68, 0xbfb8aa3b, v68
	v_mul_f32_e32 v69, 0xbfb8aa3b, v69
	v_exp_f32_e32 v68, v68
	v_exp_f32_e32 v69, v69
	s_nop 0
	v_pk_add_f32 v[68:69], v[68:69], 1.0 op_sel_hi:[1,0]
	s_nop 0
	v_div_scale_f32 v70, s[2:3], v69, v69, 1.0
	v_rcp_f32_e32 v71, v70
	s_nop 0
	v_fma_f32 v72, -v70, v71, 1.0
	v_fmac_f32_e32 v71, v72, v71
	v_div_scale_f32 v72, vcc, 1.0, v69, 1.0
	v_mul_f32_e32 v73, v72, v71
	v_fma_f32 v74, -v70, v73, v72
	v_fmac_f32_e32 v73, v74, v71
	v_fma_f32 v70, -v70, v73, v72
	v_div_fmas_f32 v70, v70, v71, v73
	v_div_fixup_f32 v69, v70, v69, 1.0
	v_div_scale_f32 v70, s[2:3], v68, v68, 1.0
	v_rcp_f32_e32 v71, v70
	s_nop 0
	v_fma_f32 v72, -v70, v71, 1.0
	v_fmac_f32_e32 v71, v72, v71
	v_div_scale_f32 v72, vcc, 1.0, v68, 1.0
	v_mul_f32_e32 v73, v72, v71
	v_fma_f32 v74, -v70, v73, v72
	v_fmac_f32_e32 v73, v74, v71
	v_fma_f32 v70, -v70, v73, v72
	v_div_fmas_f32 v70, v70, v71, v73
	v_div_fixup_f32 v68, v70, v68, 1.0
	v_pk_fma_f32 v[142:143], v[36:37], v[68:69], v[142:143]
	s_waitcnt vmcnt(30)
	v_cvt_f32_f16_e32 v68, v212
	v_cvt_f32_f16_e32 v69, v213
	v_add_u32_e32 v96, 0x91000, v94
	global_load_ushort v212, v96, s[40:41] offset:64
	v_add_u32_e32 v96, 0x94a00, v94
	global_load_ushort v213, v96, s[40:41] offset:64
	v_mul_f32_e32 v68, 0xbfb8aa3b, v68
	v_mul_f32_e32 v69, 0xbfb8aa3b, v69
	v_exp_f32_e32 v68, v68
	v_exp_f32_e32 v69, v69
	s_nop 0
	v_pk_add_f32 v[68:69], v[68:69], 1.0 op_sel_hi:[1,0]
	s_nop 0
	v_div_scale_f32 v70, s[2:3], v69, v69, 1.0
	v_rcp_f32_e32 v71, v70
	s_nop 0
	v_fma_f32 v72, -v70, v71, 1.0
	v_fmac_f32_e32 v71, v72, v71
	v_div_scale_f32 v72, vcc, 1.0, v69, 1.0
	v_mul_f32_e32 v73, v72, v71
	v_fma_f32 v74, -v70, v73, v72
	v_fmac_f32_e32 v73, v74, v71
	v_fma_f32 v70, -v70, v73, v72
	v_div_fmas_f32 v70, v70, v71, v73
	v_div_fixup_f32 v69, v70, v69, 1.0
	v_div_scale_f32 v70, s[2:3], v68, v68, 1.0
	v_rcp_f32_e32 v71, v70
	s_nop 0
	v_fma_f32 v72, -v70, v71, 1.0
	v_fmac_f32_e32 v71, v72, v71
	v_div_scale_f32 v72, vcc, 1.0, v68, 1.0
	v_mul_f32_e32 v73, v72, v71
	v_fma_f32 v74, -v70, v73, v72
	v_fmac_f32_e32 v73, v74, v71
	v_fma_f32 v70, -v70, v73, v72
	v_div_fmas_f32 v70, v70, v71, v73
	v_div_fixup_f32 v68, v70, v68, 1.0
	v_pk_fma_f32 v[140:141], v[38:39], v[68:69], v[140:141]
	s_waitcnt vmcnt(30)
; __device__ __forceinline__ float sigmoidf_(float x) { return 1.f / (1.f + __expf(-x)); }
; __device__ __forceinline__ void phase_merge(const KP& p, char* smem, int* q, int xcc) {
;     ...
;           [&](int mi, int ni, int r, int row, int col, float v) {
;             const float gz = (float)G[(size_t)row * NU + col];
;             tot[mi][ni][r] += sigmoidf_(gz) * v;
;           },
	v_cvt_f32_f16_e32 v68, v214
	v_cvt_f32_f16_e32 v69, v215
	v_add_u32_e32 v96, 0x98400, v94
	global_load_ushort v214, v96, s[40:41] offset:64
	v_add_u32_e32 v96, 0x9be00, v94
	global_load_ushort v215, v96, s[40:41] offset:64
	v_mul_f32_e32 v68, 0xbfb8aa3b, v68
	v_mul_f32_e32 v69, 0xbfb8aa3b, v69
	v_exp_f32_e32 v68, v68
	v_exp_f32_e32 v69, v69
	s_nop 0
	v_pk_add_f32 v[68:69], v[68:69], 1.0 op_sel_hi:[1,0]
	s_nop 0
	v_div_scale_f32 v70, s[2:3], v69, v69, 1.0
	v_rcp_f32_e32 v71, v70
	s_nop 0
	v_fma_f32 v72, -v70, v71, 1.0
	v_fmac_f32_e32 v71, v72, v71
	v_div_scale_f32 v72, vcc, 1.0, v69, 1.0
	v_mul_f32_e32 v73, v72, v71
	v_fma_f32 v74, -v70, v73, v72
	v_fmac_f32_e32 v73, v74, v71
	v_fma_f32 v70, -v70, v73, v72
	v_div_fmas_f32 v70, v70, v71, v73
	v_div_fixup_f32 v69, v70, v69, 1.0
	v_div_scale_f32 v70, s[2:3], v68, v68, 1.0
	v_rcp_f32_e32 v71, v70
	s_nop 0
	v_fma_f32 v72, -v70, v71, 1.0
	v_fmac_f32_e32 v71, v72, v71
	v_div_scale_f32 v72, vcc, 1.0, v68, 1.0
	v_mul_f32_e32 v73, v72, v71
	v_fma_f32 v74, -v70, v73, v72
	v_fmac_f32_e32 v73, v74, v71
	v_fma_f32 v70, -v70, v73, v72
	v_div_fmas_f32 v70, v70, v71, v73
	v_div_fixup_f32 v68, v70, v68, 1.0
	v_pk_fma_f32 v[138:139], v[40:41], v[68:69], v[138:139]
	s_waitcnt vmcnt(30)
	v_cvt_f32_f16_e32 v68, v216
	v_cvt_f32_f16_e32 v69, v217
	v_add_u32_e32 v96, 0xae000, v94
	global_load_ushort v216, v96, s[40:41] offset:64
	v_add_u32_e32 v96, 0xb1a00, v94
	global_load_ushort v217, v96, s[40:41] offset:64
	v_mul_f32_e32 v68, 0xbfb8aa3b, v68
	v_mul_f32_e32 v69, 0xbfb8aa3b, v69
	v_exp_f32_e32 v68, v68
	v_exp_f32_e32 v69, v69
	s_nop 0
	v_pk_add_f32 v[68:69], v[68:69], 1.0 op_sel_hi:[1,0]
	s_nop 0
	v_div_scale_f32 v70, s[2:3], v69, v69, 1.0
	v_rcp_f32_e32 v71, v70
	s_nop 0
	v_fma_f32 v72, -v70, v71, 1.0
	v_fmac_f32_e32 v71, v72, v71
	v_div_scale_f32 v72, vcc, 1.0, v69, 1.0
	v_mul_f32_e32 v73, v72, v71
	v_fma_f32 v74, -v70, v73, v72
	v_fmac_f32_e32 v73, v74, v71
	v_fma_f32 v70, -v70, v73, v72
	v_div_fmas_f32 v70, v70, v71, v73
	v_div_fixup_f32 v69, v70, v69, 1.0
	v_div_scale_f32 v70, s[2:3], v68, v68, 1.0
	v_rcp_f32_e32 v71, v70
	s_nop 0
	v_fma_f32 v72, -v70, v71, 1.0
	v_fmac_f32_e32 v71, v72, v71
	v_div_scale_f32 v72, vcc, 1.0, v68, 1.0
	v_mul_f32_e32 v73, v72, v71
	v_fma_f32 v74, -v70, v73, v72
	v_fmac_f32_e32 v73, v74, v71
	v_fma_f32 v70, -v70, v73, v72
	v_div_fmas_f32 v70, v70, v71, v73
	v_div_fixup_f32 v68, v70, v68, 1.0
	v_pk_fma_f32 v[136:137], v[42:43], v[68:69], v[136:137]
	s_waitcnt vmcnt(30)
	v_cvt_f32_f16_e32 v68, v218
	v_cvt_f32_f16_e32 v69, v219
	v_add_u32_e32 v96, 0xb5400, v94
	global_load_ushort v218, v96, s[40:41] offset:64
	v_add_u32_e32 v96, 0xb8e00, v94
	global_load_ushort v219, v96, s[40:41] offset:64
	v_mul_f32_e32 v68, 0xbfb8aa3b, v68
	v_mul_f32_e32 v69, 0xbfb8aa3b, v69
	v_exp_f32_e32 v68, v68
	v_exp_f32_e32 v69, v69
	s_nop 0
	v_pk_add_f32 v[68:69], v[68:69], 1.0 op_sel_hi:[1,0]
	s_nop 0
	v_div_scale_f32 v70, s[2:3], v69, v69, 1.0
	v_rcp_f32_e32 v71, v70
	s_nop 0
	v_fma_f32 v72, -v70, v71, 1.0
	v_fmac_f32_e32 v71, v72, v71
	v_div_scale_f32 v72, vcc, 1.0, v69, 1.0
	v_mul_f32_e32 v73, v72, v71
	v_fma_f32 v74, -v70, v73, v72
	v_fmac_f32_e32 v73, v74, v71
	v_fma_f32 v70, -v70, v73, v72
	v_div_fmas_f32 v70, v70, v71, v73
	v_div_fixup_f32 v69, v70, v69, 1.0
	v_div_scale_f32 v70, s[2:3], v68, v68, 1.0
	v_rcp_f32_e32 v71, v70
	s_nop 0
	v_fma_f32 v72, -v70, v71, 1.0
	v_fmac_f32_e32 v71, v72, v71
	v_div_scale_f32 v72, vcc, 1.0, v68, 1.0
	v_mul_f32_e32 v73, v72, v71
	v_fma_f32 v74, -v70, v73, v72
	v_fmac_f32_e32 v73, v74, v71
	v_fma_f32 v70, -v70, v73, v72
	v_div_fmas_f32 v70, v70, v71, v73
	v_div_fixup_f32 v68, v70, v68, 1.0
	v_pk_fma_f32 v[134:135], v[44:45], v[68:69], v[134:135]
	s_waitcnt vmcnt(30)
	v_cvt_f32_f16_e32 v68, v220
	v_cvt_f32_f16_e32 v69, v221
	v_add_u32_e32 v96, 0xcb000, v94
	global_load_ushort v220, v96, s[40:41] offset:64
	v_add_u32_e32 v96, 0xcea00, v94
	global_load_ushort v221, v96, s[40:41] offset:64
	v_mul_f32_e32 v68, 0xbfb8aa3b, v68
	v_mul_f32_e32 v69, 0xbfb8aa3b, v69
	v_exp_f32_e32 v68, v68
	v_exp_f32_e32 v69, v69
	s_nop 0
	v_pk_add_f32 v[68:69], v[68:69], 1.0 op_sel_hi:[1,0]
	s_nop 0
	v_div_scale_f32 v70, s[2:3], v69, v69, 1.0
	v_rcp_f32_e32 v71, v70
	s_nop 0
	v_fma_f32 v72, -v70, v71, 1.0
	v_fmac_f32_e32 v71, v72, v71
	v_div_scale_f32 v72, vcc, 1.0, v69, 1.0
	v_mul_f32_e32 v73, v72, v71
	v_fma_f32 v74, -v70, v73, v72
	v_fmac_f32_e32 v73, v74, v71
	v_fma_f32 v70, -v70, v73, v72
	v_div_fmas_f32 v70, v70, v71, v73
	v_div_fixup_f32 v69, v70, v69, 1.0
	v_div_scale_f32 v70, s[2:3], v68, v68, 1.0
	v_rcp_f32_e32 v71, v70
	s_nop 0
	v_fma_f32 v72, -v70, v71, 1.0
	v_fmac_f32_e32 v71, v72, v71
	v_div_scale_f32 v72, vcc, 1.0, v68, 1.0
	v_mul_f32_e32 v73, v72, v71
	v_fma_f32 v74, -v70, v73, v72
	v_fmac_f32_e32 v73, v74, v71
	v_fma_f32 v70, -v70, v73, v72
	v_div_fmas_f32 v70, v70, v71, v73
	v_div_fixup_f32 v68, v70, v68, 1.0
	v_pk_fma_f32 v[132:133], v[46:47], v[68:69], v[132:133]
	s_waitcnt vmcnt(30)
	v_cvt_f32_f16_e32 v68, v222
	v_cvt_f32_f16_e32 v69, v223
	v_add_u32_e32 v96, 0xd2400, v94
	global_load_ushort v222, v96, s[40:41] offset:64
	v_add_u32_e32 v96, 0xd5e00, v94
	global_load_ushort v223, v96, s[40:41] offset:64
	v_mul_f32_e32 v68, 0xbfb8aa3b, v68
	v_mul_f32_e32 v69, 0xbfb8aa3b, v69
	v_exp_f32_e32 v68, v68
	v_exp_f32_e32 v69, v69
	s_nop 0
	v_pk_add_f32 v[68:69], v[68:69], 1.0 op_sel_hi:[1,0]
	s_nop 0
	v_div_scale_f32 v70, s[2:3], v69, v69, 1.0
	v_rcp_f32_e32 v71, v70
	s_nop 0
	v_fma_f32 v72, -v70, v71, 1.0
	v_fmac_f32_e32 v71, v72, v71
	v_div_scale_f32 v72, vcc, 1.0, v69, 1.0
	v_mul_f32_e32 v73, v72, v71
	v_fma_f32 v74, -v70, v73, v72
	v_fmac_f32_e32 v73, v74, v71
	v_fma_f32 v70, -v70, v73, v72
	v_div_fmas_f32 v70, v70, v71, v73
	v_div_fixup_f32 v69, v70, v69, 1.0
	v_div_scale_f32 v70, s[2:3], v68, v68, 1.0
	v_rcp_f32_e32 v71, v70
	s_nop 0
	v_fma_f32 v72, -v70, v71, 1.0
	v_fmac_f32_e32 v71, v72, v71
	v_div_scale_f32 v72, vcc, 1.0, v68, 1.0
	v_mul_f32_e32 v73, v72, v71
	v_fma_f32 v74, -v70, v73, v72
	v_fmac_f32_e32 v73, v74, v71
	v_fma_f32 v70, -v70, v73, v72
	v_div_fmas_f32 v70, v70, v71, v73
	v_div_fixup_f32 v68, v70, v68, 1.0
	v_pk_fma_f32 v[130:131], v[48:49], v[68:69], v[130:131]
	s_waitcnt vmcnt(30)
; __device__ __forceinline__ float sigmoidf_(float x) { return 1.f / (1.f + __expf(-x)); }
; __device__ __forceinline__ void phase_merge(const KP& p, char* smem, int* q, int xcc) {
;     ...
;           [&](int mi, int ni, int r, int row, int col, float v) {
;             const float gz = (float)G[(size_t)row * NU + col];
;             tot[mi][ni][r] += sigmoidf_(gz) * v;
;           },
	v_cvt_f32_f16_e32 v68, v192
	v_cvt_f32_f16_e32 v69, v193
	v_mul_f32_e32 v68, 0xbfb8aa3b, v68
	v_mul_f32_e32 v69, 0xbfb8aa3b, v69
	v_exp_f32_e32 v68, v68
	v_exp_f32_e32 v69, v69
	s_nop 0
	v_pk_add_f32 v[68:69], v[68:69], 1.0 op_sel_hi:[1,0]
	s_nop 0
	v_div_scale_f32 v70, s[2:3], v69, v69, 1.0
	v_rcp_f32_e32 v71, v70
	s_nop 0
	v_fma_f32 v72, -v70, v71, 1.0
	v_fmac_f32_e32 v71, v72, v71
	v_div_scale_f32 v72, vcc, 1.0, v69, 1.0
	v_mul_f32_e32 v73, v72, v71
	v_fma_f32 v74, -v70, v73, v72
	v_fmac_f32_e32 v73, v74, v71
	v_fma_f32 v70, -v70, v73, v72
	v_div_fmas_f32 v70, v70, v71, v73
	v_div_fixup_f32 v69, v70, v69, 1.0
	v_div_scale_f32 v70, s[2:3], v68, v68, 1.0
	v_rcp_f32_e32 v71, v70
	s_nop 0
	v_fma_f32 v72, -v70, v71, 1.0
	v_fmac_f32_e32 v71, v72, v71
	v_div_scale_f32 v72, vcc, 1.0, v68, 1.0
	v_mul_f32_e32 v73, v72, v71
	v_fma_f32 v74, -v70, v73, v72
	v_fmac_f32_e32 v73, v74, v71
	v_fma_f32 v70, -v70, v73, v72
	v_div_fmas_f32 v70, v70, v71, v73
	v_div_fixup_f32 v68, v70, v68, 1.0
	v_pk_fma_f32 v[128:129], v[18:19], v[68:69], v[128:129]
	s_waitcnt vmcnt(28)
	v_cvt_f32_f16_e32 v68, v194
	v_cvt_f32_f16_e32 v69, v195
	v_mul_f32_e32 v68, 0xbfb8aa3b, v68
	v_mul_f32_e32 v69, 0xbfb8aa3b, v69
	v_exp_f32_e32 v68, v68
	v_exp_f32_e32 v69, v69
	s_nop 0
	v_pk_add_f32 v[68:69], v[68:69], 1.0 op_sel_hi:[1,0]
	s_nop 0
	v_div_scale_f32 v70, s[2:3], v69, v69, 1.0
	v_rcp_f32_e32 v71, v70
	s_nop 0
	v_fma_f32 v72, -v70, v71, 1.0
	v_fmac_f32_e32 v71, v72, v71
	v_div_scale_f32 v72, vcc, 1.0, v69, 1.0
	v_mul_f32_e32 v73, v72, v71
	v_fma_f32 v74, -v70, v73, v72
	v_fmac_f32_e32 v73, v74, v71
	v_fma_f32 v70, -v70, v73, v72
	v_div_fmas_f32 v70, v70, v71, v73
	v_div_fixup_f32 v69, v70, v69, 1.0
	v_div_scale_f32 v70, s[2:3], v68, v68, 1.0
	v_rcp_f32_e32 v71, v70
	s_nop 0
	v_fma_f32 v72, -v70, v71, 1.0
	v_fmac_f32_e32 v71, v72, v71
	v_div_scale_f32 v72, vcc, 1.0, v68, 1.0
	v_mul_f32_e32 v73, v72, v71
	v_fma_f32 v74, -v70, v73, v72
	v_fmac_f32_e32 v73, v74, v71
	v_fma_f32 v70, -v70, v73, v72
	v_div_fmas_f32 v70, v70, v71, v73
	v_div_fixup_f32 v68, v70, v68, 1.0
	v_pk_fma_f32 v[126:127], v[20:21], v[68:69], v[126:127]
	s_waitcnt vmcnt(26)
	v_cvt_f32_f16_e32 v68, v196
	v_cvt_f32_f16_e32 v69, v197
	v_mul_f32_e32 v68, 0xbfb8aa3b, v68
	v_mul_f32_e32 v69, 0xbfb8aa3b, v69
	v_exp_f32_e32 v68, v68
	v_exp_f32_e32 v69, v69
	s_nop 0
	v_pk_add_f32 v[68:69], v[68:69], 1.0 op_sel_hi:[1,0]
	s_nop 0
	v_div_scale_f32 v70, s[2:3], v69, v69, 1.0
	v_rcp_f32_e32 v71, v70
	s_nop 0
	v_fma_f32 v72, -v70, v71, 1.0
	v_fmac_f32_e32 v71, v72, v71
	v_div_scale_f32 v72, vcc, 1.0, v69, 1.0
	v_mul_f32_e32 v73, v72, v71
	v_fma_f32 v74, -v70, v73, v72
	v_fmac_f32_e32 v73, v74, v71
	v_fma_f32 v70, -v70, v73, v72
	v_div_fmas_f32 v70, v70, v71, v73
	v_div_fixup_f32 v69, v70, v69, 1.0
	v_div_scale_f32 v70, s[2:3], v68, v68, 1.0
	v_rcp_f32_e32 v71, v70
	s_nop 0
	v_fma_f32 v72, -v70, v71, 1.0
	v_fmac_f32_e32 v71, v72, v71
	v_div_scale_f32 v72, vcc, 1.0, v68, 1.0
	v_mul_f32_e32 v73, v72, v71
	v_fma_f32 v74, -v70, v73, v72
	v_fmac_f32_e32 v73, v74, v71
	v_fma_f32 v70, -v70, v73, v72
	v_div_fmas_f32 v70, v70, v71, v73
	v_div_fixup_f32 v68, v70, v68, 1.0
	v_pk_fma_f32 v[124:125], v[22:23], v[68:69], v[124:125]
	s_waitcnt vmcnt(24)
	v_cvt_f32_f16_e32 v68, v198
	v_cvt_f32_f16_e32 v69, v199
	v_mul_f32_e32 v68, 0xbfb8aa3b, v68
	v_mul_f32_e32 v69, 0xbfb8aa3b, v69
	v_exp_f32_e32 v68, v68
	v_exp_f32_e32 v69, v69
	s_nop 0
	v_pk_add_f32 v[68:69], v[68:69], 1.0 op_sel_hi:[1,0]
	s_nop 0
	v_div_scale_f32 v70, s[2:3], v69, v69, 1.0
	v_rcp_f32_e32 v71, v70
	s_nop 0
	v_fma_f32 v72, -v70, v71, 1.0
	v_fmac_f32_e32 v71, v72, v71
	v_div_scale_f32 v72, vcc, 1.0, v69, 1.0
	v_mul_f32_e32 v73, v72, v71
	v_fma_f32 v74, -v70, v73, v72
	v_fmac_f32_e32 v73, v74, v71
	v_fma_f32 v70, -v70, v73, v72
	v_div_fmas_f32 v70, v70, v71, v73
	v_div_fixup_f32 v69, v70, v69, 1.0
	v_div_scale_f32 v70, s[2:3], v68, v68, 1.0
	v_rcp_f32_e32 v71, v70
	s_nop 0
	v_fma_f32 v72, -v70, v71, 1.0
	v_fmac_f32_e32 v71, v72, v71
	v_div_scale_f32 v72, vcc, 1.0, v68, 1.0
	v_mul_f32_e32 v73, v72, v71
	v_fma_f32 v74, -v70, v73, v72
	v_fmac_f32_e32 v73, v74, v71
	v_fma_f32 v70, -v70, v73, v72
	v_div_fmas_f32 v70, v70, v71, v73
	v_div_fixup_f32 v68, v70, v68, 1.0
	v_pk_fma_f32 v[122:123], v[24:25], v[68:69], v[122:123]
	s_waitcnt vmcnt(22)
	v_cvt_f32_f16_e32 v68, v200
	v_cvt_f32_f16_e32 v69, v201
	v_mul_f32_e32 v68, 0xbfb8aa3b, v68
	v_mul_f32_e32 v69, 0xbfb8aa3b, v69
	v_exp_f32_e32 v68, v68
	v_exp_f32_e32 v69, v69
	s_nop 0
	v_pk_add_f32 v[68:69], v[68:69], 1.0 op_sel_hi:[1,0]
	s_nop 0
	v_div_scale_f32 v70, s[2:3], v69, v69, 1.0
	v_rcp_f32_e32 v71, v70
	s_nop 0
	v_fma_f32 v72, -v70, v71, 1.0
	v_fmac_f32_e32 v71, v72, v71
	v_div_scale_f32 v72, vcc, 1.0, v69, 1.0
	v_mul_f32_e32 v73, v72, v71
	v_fma_f32 v74, -v70, v73, v72
	v_fmac_f32_e32 v73, v74, v71
	v_fma_f32 v70, -v70, v73, v72
	v_div_fmas_f32 v70, v70, v71, v73
	v_div_fixup_f32 v69, v70, v69, 1.0
	v_div_scale_f32 v70, s[2:3], v68, v68, 1.0
	v_rcp_f32_e32 v71, v70
	s_nop 0
	v_fma_f32 v72, -v70, v71, 1.0
	v_fmac_f32_e32 v71, v72, v71
	v_div_scale_f32 v72, vcc, 1.0, v68, 1.0
	v_mul_f32_e32 v73, v72, v71
	v_fma_f32 v74, -v70, v73, v72
	v_fmac_f32_e32 v73, v74, v71
	v_fma_f32 v70, -v70, v73, v72
	v_div_fmas_f32 v70, v70, v71, v73
	v_div_fixup_f32 v68, v70, v68, 1.0
	v_pk_fma_f32 v[120:121], v[26:27], v[68:69], v[120:121]
	s_waitcnt vmcnt(20)
; __device__ __forceinline__ float sigmoidf_(float x) { return 1.f / (1.f + __expf(-x)); }
; __device__ __forceinline__ void phase_merge(const KP& p, char* smem, int* q, int xcc) {
;     ...
;           [&](int mi, int ni, int r, int row, int col, float v) {
;             const float gz = (float)G[(size_t)row * NU + col];
;             tot[mi][ni][r] += sigmoidf_(gz) * v;
;           },
	v_cvt_f32_f16_e32 v68, v202
	v_cvt_f32_f16_e32 v69, v203
	v_mul_f32_e32 v68, 0xbfb8aa3b, v68
	v_mul_f32_e32 v69, 0xbfb8aa3b, v69
	v_exp_f32_e32 v68, v68
	v_exp_f32_e32 v69, v69
	s_nop 0
	v_pk_add_f32 v[68:69], v[68:69], 1.0 op_sel_hi:[1,0]
	s_nop 0
	v_div_scale_f32 v70, s[2:3], v69, v69, 1.0
	v_rcp_f32_e32 v71, v70
	s_nop 0
	v_fma_f32 v72, -v70, v71, 1.0
	v_fmac_f32_e32 v71, v72, v71
	v_div_scale_f32 v72, vcc, 1.0, v69, 1.0
	v_mul_f32_e32 v73, v72, v71
	v_fma_f32 v74, -v70, v73, v72
	v_fmac_f32_e32 v73, v74, v71
	v_fma_f32 v70, -v70, v73, v72
	v_div_fmas_f32 v70, v70, v71, v73
	v_div_fixup_f32 v69, v70, v69, 1.0
	v_div_scale_f32 v70, s[2:3], v68, v68, 1.0
	v_rcp_f32_e32 v71, v70
	s_nop 0
	v_fma_f32 v72, -v70, v71, 1.0
	v_fmac_f32_e32 v71, v72, v71
	v_div_scale_f32 v72, vcc, 1.0, v68, 1.0
	v_mul_f32_e32 v73, v72, v71
	v_fma_f32 v74, -v70, v73, v72
	v_fmac_f32_e32 v73, v74, v71
	v_fma_f32 v70, -v70, v73, v72
	v_div_fmas_f32 v70, v70, v71, v73
	v_div_fixup_f32 v68, v70, v68, 1.0
	v_pk_fma_f32 v[118:119], v[28:29], v[68:69], v[118:119]
	s_waitcnt vmcnt(18)
	v_cvt_f32_f16_e32 v68, v204
	v_cvt_f32_f16_e32 v69, v205
	v_mul_f32_e32 v68, 0xbfb8aa3b, v68
	v_mul_f32_e32 v69, 0xbfb8aa3b, v69
	v_exp_f32_e32 v68, v68
	v_exp_f32_e32 v69, v69
	s_nop 0
	v_pk_add_f32 v[68:69], v[68:69], 1.0 op_sel_hi:[1,0]
	s_nop 0
	v_div_scale_f32 v70, s[2:3], v69, v69, 1.0
	v_rcp_f32_e32 v71, v70
	s_nop 0
	v_fma_f32 v72, -v70, v71, 1.0
	v_fmac_f32_e32 v71, v72, v71
	v_div_scale_f32 v72, vcc, 1.0, v69, 1.0
	v_mul_f32_e32 v73, v72, v71
	v_fma_f32 v74, -v70, v73, v72
	v_fmac_f32_e32 v73, v74, v71
	v_fma_f32 v70, -v70, v73, v72
	v_div_fmas_f32 v70, v70, v71, v73
	v_div_fixup_f32 v69, v70, v69, 1.0
	v_div_scale_f32 v70, s[2:3], v68, v68, 1.0
	v_rcp_f32_e32 v71, v70
	s_nop 0
	v_fma_f32 v72, -v70, v71, 1.0
	v_fmac_f32_e32 v71, v72, v71
	v_div_scale_f32 v72, vcc, 1.0, v68, 1.0
	v_mul_f32_e32 v73, v72, v71
	v_fma_f32 v74, -v70, v73, v72
	v_fmac_f32_e32 v73, v74, v71
	v_fma_f32 v70, -v70, v73, v72
	v_div_fmas_f32 v70, v70, v71, v73
	v_div_fixup_f32 v68, v70, v68, 1.0
	v_pk_fma_f32 v[116:117], v[30:31], v[68:69], v[116:117]
	s_waitcnt vmcnt(16)
	v_cvt_f32_f16_e32 v68, v206
	v_cvt_f32_f16_e32 v69, v207
	v_mul_f32_e32 v68, 0xbfb8aa3b, v68
	v_mul_f32_e32 v69, 0xbfb8aa3b, v69
	v_exp_f32_e32 v68, v68
	v_exp_f32_e32 v69, v69
	s_nop 0
	v_pk_add_f32 v[68:69], v[68:69], 1.0 op_sel_hi:[1,0]
	s_nop 0
	v_div_scale_f32 v70, s[2:3], v69, v69, 1.0
	v_rcp_f32_e32 v71, v70
	s_nop 0
	v_fma_f32 v72, -v70, v71, 1.0
	v_fmac_f32_e32 v71, v72, v71
	v_div_scale_f32 v72, vcc, 1.0, v69, 1.0
	v_mul_f32_e32 v73, v72, v71
	v_fma_f32 v74, -v70, v73, v72
	v_fmac_f32_e32 v73, v74, v71
	v_fma_f32 v70, -v70, v73, v72
	v_div_fmas_f32 v70, v70, v71, v73
	v_div_fixup_f32 v69, v70, v69, 1.0
	v_div_scale_f32 v70, s[2:3], v68, v68, 1.0
	v_rcp_f32_e32 v71, v70
	s_nop 0
	v_fma_f32 v72, -v70, v71, 1.0
	v_fmac_f32_e32 v71, v72, v71
	v_div_scale_f32 v72, vcc, 1.0, v68, 1.0
	v_mul_f32_e32 v73, v72, v71
	v_fma_f32 v74, -v70, v73, v72
	v_fmac_f32_e32 v73, v74, v71
	v_fma_f32 v70, -v70, v73, v72
	v_div_fmas_f32 v70, v70, v71, v73
	v_div_fixup_f32 v68, v70, v68, 1.0
	v_pk_fma_f32 v[114:115], v[32:33], v[68:69], v[114:115]
	s_waitcnt vmcnt(14)
	v_cvt_f32_f16_e32 v68, v208
	v_cvt_f32_f16_e32 v69, v209
	v_mul_f32_e32 v68, 0xbfb8aa3b, v68
	v_mul_f32_e32 v69, 0xbfb8aa3b, v69
	v_exp_f32_e32 v68, v68
	v_exp_f32_e32 v69, v69
	s_nop 0
	v_pk_add_f32 v[68:69], v[68:69], 1.0 op_sel_hi:[1,0]
	s_nop 0
	v_div_scale_f32 v70, s[2:3], v69, v69, 1.0
	v_rcp_f32_e32 v71, v70
	s_nop 0
	v_fma_f32 v72, -v70, v71, 1.0
	v_fmac_f32_e32 v71, v72, v71
	v_div_scale_f32 v72, vcc, 1.0, v69, 1.0
	v_mul_f32_e32 v73, v72, v71
	v_fma_f32 v74, -v70, v73, v72
	v_fmac_f32_e32 v73, v74, v71
	v_fma_f32 v70, -v70, v73, v72
	v_div_fmas_f32 v70, v70, v71, v73
	v_div_fixup_f32 v69, v70, v69, 1.0
	v_div_scale_f32 v70, s[2:3], v68, v68, 1.0
	v_rcp_f32_e32 v71, v70
	s_nop 0
	v_fma_f32 v72, -v70, v71, 1.0
	v_fmac_f32_e32 v71, v72, v71
	v_div_scale_f32 v72, vcc, 1.0, v68, 1.0
	v_mul_f32_e32 v73, v72, v71
	v_fma_f32 v74, -v70, v73, v72
	v_fmac_f32_e32 v73, v74, v71
	v_fma_f32 v70, -v70, v73, v72
	v_div_fmas_f32 v70, v70, v71, v73
	v_div_fixup_f32 v68, v70, v68, 1.0
	v_pk_fma_f32 v[112:113], v[2:3], v[68:69], v[112:113]
	s_waitcnt vmcnt(12)
	v_cvt_f32_f16_e32 v68, v210
	v_cvt_f32_f16_e32 v69, v211
	v_mul_f32_e32 v68, 0xbfb8aa3b, v68
	v_mul_f32_e32 v69, 0xbfb8aa3b, v69
	v_exp_f32_e32 v68, v68
	v_exp_f32_e32 v69, v69
	s_nop 0
	v_pk_add_f32 v[68:69], v[68:69], 1.0 op_sel_hi:[1,0]
	s_nop 0
	v_div_scale_f32 v70, s[2:3], v69, v69, 1.0
	v_rcp_f32_e32 v71, v70
	s_nop 0
	v_fma_f32 v72, -v70, v71, 1.0
	v_fmac_f32_e32 v71, v72, v71
	v_div_scale_f32 v72, vcc, 1.0, v69, 1.0
	v_mul_f32_e32 v73, v72, v71
	v_fma_f32 v74, -v70, v73, v72
	v_fmac_f32_e32 v73, v74, v71
	v_fma_f32 v70, -v70, v73, v72
	v_div_fmas_f32 v70, v70, v71, v73
	v_div_fixup_f32 v69, v70, v69, 1.0
	v_div_scale_f32 v70, s[2:3], v68, v68, 1.0
	v_rcp_f32_e32 v71, v70
	s_nop 0
	v_fma_f32 v72, -v70, v71, 1.0
	v_fmac_f32_e32 v71, v72, v71
	v_div_scale_f32 v72, vcc, 1.0, v68, 1.0
	v_mul_f32_e32 v73, v72, v71
	v_fma_f32 v74, -v70, v73, v72
	v_fmac_f32_e32 v73, v74, v71
	v_fma_f32 v70, -v70, v73, v72
	v_div_fmas_f32 v70, v70, v71, v73
	v_div_fixup_f32 v68, v70, v68, 1.0
	v_pk_fma_f32 v[110:111], v[4:5], v[68:69], v[110:111]
	s_waitcnt vmcnt(10)
;   __device__ __forceinline__ half_t* u() const { return (half_t*)(ws() + OFF_u); }
;   __device__ __forceinline__ half_t* wpT() const { return (half_t*)(ws() + OFF_wpT); }
;   __device__ __forceinline__ half_t* ya() const { return (half_t*)(ws() + OFF_ya); }
;   __device__ __forceinline__ half_t* yb() const { return (half_t*)(ws() + OFF_yb); }
;   __device__ __forceinline__ half_t* yc() const { return (half_t*)(ws() + OFF_yc); }
; __device__ __forceinline__ float sigmoidf_(float x) { return 1.f / (1.f + __expf(-x)); }
; __device__ __forceinline__ void phase_merge(const KP& p, char* smem, int* q, int xcc) {
;     ...
;     for (int br = 0; br < 3; ++br) {
;       const half_t* A = (br == 0 ? p.ya() : (br == 1 ? p.yb() : p.yc())) + (size_t)m0 * 512;
;       const half_t* B = p.wpT() + (size_t)br * DM * 512 + (size_t)n0 * 512;
;       const half_t* G = p.u() + (size_t)m0 * NU + C_GM + br * 1024 + n0;
;       gemm_tile<2>(
;           512, [&](int r, int k) { return *(const uint4*)(A + (size_t)r * 512 + k); },
;           [&](int r, int k) { return *(const uint4*)(B + (size_t)r * 512 + k); },
;           [&](int mi, int ni, int r, int row, int col, float v) {
;             const float gz = (float)G[(size_t)row * NU + col];
;             tot[mi][ni][r] += sigmoidf_(gz) * v;
;           },
;           smem);
;     }
	v_cvt_f32_f16_e32 v68, v212
	v_cvt_f32_f16_e32 v69, v213
	v_mul_f32_e32 v68, 0xbfb8aa3b, v68
	v_mul_f32_e32 v69, 0xbfb8aa3b, v69
	v_exp_f32_e32 v68, v68
	v_exp_f32_e32 v69, v69
	s_nop 0
	v_pk_add_f32 v[68:69], v[68:69], 1.0 op_sel_hi:[1,0]
	s_nop 0
	v_div_scale_f32 v70, s[2:3], v69, v69, 1.0
	v_rcp_f32_e32 v71, v70
	s_nop 0
	v_fma_f32 v72, -v70, v71, 1.0
	v_fmac_f32_e32 v71, v72, v71
	v_div_scale_f32 v72, vcc, 1.0, v69, 1.0
	v_mul_f32_e32 v73, v72, v71
	v_fma_f32 v74, -v70, v73, v72
	v_fmac_f32_e32 v73, v74, v71
	v_fma_f32 v70, -v70, v73, v72
	v_div_fmas_f32 v70, v70, v71, v73
	v_div_fixup_f32 v69, v70, v69, 1.0
	v_div_scale_f32 v70, s[2:3], v68, v68, 1.0
	v_rcp_f32_e32 v71, v70
	s_nop 0
	v_fma_f32 v72, -v70, v71, 1.0
	v_fmac_f32_e32 v71, v72, v71
	v_div_scale_f32 v72, vcc, 1.0, v68, 1.0
	v_mul_f32_e32 v73, v72, v71
	v_fma_f32 v74, -v70, v73, v72
	v_fmac_f32_e32 v73, v74, v71
	v_fma_f32 v70, -v70, v73, v72
	v_div_fmas_f32 v70, v70, v71, v73
	v_div_fixup_f32 v68, v70, v68, 1.0
	v_pk_fma_f32 v[108:109], v[6:7], v[68:69], v[108:109]
	s_waitcnt vmcnt(8)
	v_cvt_f32_f16_e32 v68, v214
	v_cvt_f32_f16_e32 v69, v215
	v_mul_f32_e32 v68, 0xbfb8aa3b, v68
	v_mul_f32_e32 v69, 0xbfb8aa3b, v69
	v_exp_f32_e32 v68, v68
	v_exp_f32_e32 v69, v69
	s_nop 0
	v_pk_add_f32 v[68:69], v[68:69], 1.0 op_sel_hi:[1,0]
	s_nop 0
	v_div_scale_f32 v70, s[2:3], v69, v69, 1.0
	v_rcp_f32_e32 v71, v70
	s_nop 0
	v_fma_f32 v72, -v70, v71, 1.0
	v_fmac_f32_e32 v71, v72, v71
	v_div_scale_f32 v72, vcc, 1.0, v69, 1.0
	v_mul_f32_e32 v73, v72, v71
	v_fma_f32 v74, -v70, v73, v72
	v_fmac_f32_e32 v73, v74, v71
	v_fma_f32 v70, -v70, v73, v72
	v_div_fmas_f32 v70, v70, v71, v73
	v_div_fixup_f32 v69, v70, v69, 1.0
	v_div_scale_f32 v70, s[2:3], v68, v68, 1.0
	v_rcp_f32_e32 v71, v70
	s_nop 0
	v_fma_f32 v72, -v70, v71, 1.0
	v_fmac_f32_e32 v71, v72, v71
	v_div_scale_f32 v72, vcc, 1.0, v68, 1.0
	v_mul_f32_e32 v73, v72, v71
	v_fma_f32 v74, -v70, v73, v72
	v_fmac_f32_e32 v73, v74, v71
	v_fma_f32 v70, -v70, v73, v72
	v_div_fmas_f32 v70, v70, v71, v73
	v_div_fixup_f32 v68, v70, v68, 1.0
	v_pk_fma_f32 v[106:107], v[8:9], v[68:69], v[106:107]
	s_waitcnt vmcnt(6)
	v_cvt_f32_f16_e32 v68, v216
	v_cvt_f32_f16_e32 v69, v217
	v_mul_f32_e32 v68, 0xbfb8aa3b, v68
	v_mul_f32_e32 v69, 0xbfb8aa3b, v69
	v_exp_f32_e32 v68, v68
	v_exp_f32_e32 v69, v69
	s_nop 0
	v_pk_add_f32 v[68:69], v[68:69], 1.0 op_sel_hi:[1,0]
	s_nop 0
	v_div_scale_f32 v70, s[2:3], v69, v69, 1.0
	v_rcp_f32_e32 v71, v70
	s_nop 0
	v_fma_f32 v72, -v70, v71, 1.0
	v_fmac_f32_e32 v71, v72, v71
	v_div_scale_f32 v72, vcc, 1.0, v69, 1.0
	v_mul_f32_e32 v73, v72, v71
	v_fma_f32 v74, -v70, v73, v72
	v_fmac_f32_e32 v73, v74, v71
	v_fma_f32 v70, -v70, v73, v72
	v_div_fmas_f32 v70, v70, v71, v73
	v_div_fixup_f32 v69, v70, v69, 1.0
	v_div_scale_f32 v70, s[2:3], v68, v68, 1.0
	v_rcp_f32_e32 v71, v70
	s_nop 0
	v_fma_f32 v72, -v70, v71, 1.0
	v_fmac_f32_e32 v71, v72, v71
	v_div_scale_f32 v72, vcc, 1.0, v68, 1.0
	v_mul_f32_e32 v73, v72, v71
	v_fma_f32 v74, -v70, v73, v72
	v_fmac_f32_e32 v73, v74, v71
	v_fma_f32 v70, -v70, v73, v72
	v_div_fmas_f32 v70, v70, v71, v73
	v_div_fixup_f32 v68, v70, v68, 1.0
	v_pk_fma_f32 v[104:105], v[10:11], v[68:69], v[104:105]
	s_waitcnt vmcnt(4)
	v_cvt_f32_f16_e32 v68, v218
	v_cvt_f32_f16_e32 v69, v219
	v_mul_f32_e32 v68, 0xbfb8aa3b, v68
	v_mul_f32_e32 v69, 0xbfb8aa3b, v69
	v_exp_f32_e32 v68, v68
	v_exp_f32_e32 v69, v69
	s_nop 0
	v_pk_add_f32 v[68:69], v[68:69], 1.0 op_sel_hi:[1,0]
	s_nop 0
	v_div_scale_f32 v70, s[2:3], v69, v69, 1.0
	v_rcp_f32_e32 v71, v70
	s_nop 0
	v_fma_f32 v72, -v70, v71, 1.0
	v_fmac_f32_e32 v71, v72, v71
	v_div_scale_f32 v72, vcc, 1.0, v69, 1.0
	v_mul_f32_e32 v73, v72, v71
	v_fma_f32 v74, -v70, v73, v72
	v_fmac_f32_e32 v73, v74, v71
	v_fma_f32 v70, -v70, v73, v72
	v_div_fmas_f32 v70, v70, v71, v73
	v_div_fixup_f32 v69, v70, v69, 1.0
	v_div_scale_f32 v70, s[2:3], v68, v68, 1.0
	v_rcp_f32_e32 v71, v70
	s_nop 0
	v_fma_f32 v72, -v70, v71, 1.0
	v_fmac_f32_e32 v71, v72, v71
	v_div_scale_f32 v72, vcc, 1.0, v68, 1.0
	v_mul_f32_e32 v73, v72, v71
	v_fma_f32 v74, -v70, v73, v72
	v_fmac_f32_e32 v73, v74, v71
	v_fma_f32 v70, -v70, v73, v72
	v_div_fmas_f32 v70, v70, v71, v73
	v_div_fixup_f32 v68, v70, v68, 1.0
	v_pk_fma_f32 v[102:103], v[12:13], v[68:69], v[102:103]
	s_waitcnt vmcnt(2)
	v_cvt_f32_f16_e32 v68, v220
	v_cvt_f32_f16_e32 v69, v221
	v_mul_f32_e32 v68, 0xbfb8aa3b, v68
	v_mul_f32_e32 v69, 0xbfb8aa3b, v69
	v_exp_f32_e32 v68, v68
	v_exp_f32_e32 v69, v69
	s_nop 0
	v_pk_add_f32 v[68:69], v[68:69], 1.0 op_sel_hi:[1,0]
	s_nop 0
	v_div_scale_f32 v70, s[2:3], v69, v69, 1.0
	v_rcp_f32_e32 v71, v70
	s_nop 0
	v_fma_f32 v72, -v70, v71, 1.0
	v_fmac_f32_e32 v71, v72, v71
	v_div_scale_f32 v72, vcc, 1.0, v69, 1.0
	v_mul_f32_e32 v73, v72, v71
	v_fma_f32 v74, -v70, v73, v72
	v_fmac_f32_e32 v73, v74, v71
	v_fma_f32 v70, -v70, v73, v72
	v_div_fmas_f32 v70, v70, v71, v73
	v_div_fixup_f32 v69, v70, v69, 1.0
	v_div_scale_f32 v70, s[2:3], v68, v68, 1.0
	v_rcp_f32_e32 v71, v70
	s_nop 0
	v_fma_f32 v72, -v70, v71, 1.0
	v_fmac_f32_e32 v71, v72, v71
	v_div_scale_f32 v72, vcc, 1.0, v68, 1.0
	v_mul_f32_e32 v73, v72, v71
	v_fma_f32 v74, -v70, v73, v72
	v_fmac_f32_e32 v73, v74, v71
	v_fma_f32 v70, -v70, v73, v72
	v_div_fmas_f32 v70, v70, v71, v73
	v_div_fixup_f32 v68, v70, v68, 1.0
	v_pk_fma_f32 v[100:101], v[14:15], v[68:69], v[100:101]
	s_waitcnt vmcnt(0)
	v_cvt_f32_f16_e32 v68, v222
	v_cvt_f32_f16_e32 v69, v223
	v_mul_f32_e32 v68, 0xbfb8aa3b, v68
	v_mul_f32_e32 v69, 0xbfb8aa3b, v69
	v_exp_f32_e32 v68, v68
	v_exp_f32_e32 v69, v69
	s_nop 0
	v_pk_add_f32 v[68:69], v[68:69], 1.0 op_sel_hi:[1,0]
	s_nop 0
	v_div_scale_f32 v70, s[2:3], v69, v69, 1.0
	v_rcp_f32_e32 v71, v70
	s_nop 0
	v_fma_f32 v72, -v70, v71, 1.0
	v_fmac_f32_e32 v71, v72, v71
	v_div_scale_f32 v72, vcc, 1.0, v69, 1.0
	v_mul_f32_e32 v73, v72, v71
	v_fma_f32 v74, -v70, v73, v72
	v_fmac_f32_e32 v73, v74, v71
	v_fma_f32 v70, -v70, v73, v72
	v_div_fmas_f32 v70, v70, v71, v73
	v_div_fixup_f32 v69, v70, v69, 1.0
	v_div_scale_f32 v70, s[2:3], v68, v68, 1.0
	v_rcp_f32_e32 v71, v70
	s_nop 0
	v_fma_f32 v72, -v70, v71, 1.0
	v_fmac_f32_e32 v71, v72, v71
	v_div_scale_f32 v72, vcc, 1.0, v68, 1.0
	v_mul_f32_e32 v73, v72, v71
	v_fma_f32 v74, -v70, v73, v72
	v_fmac_f32_e32 v73, v74, v71
	v_fma_f32 v70, -v70, v73, v72
	v_div_fmas_f32 v70, v70, v71, v73
	v_div_fixup_f32 v68, v70, v68, 1.0
	v_pk_fma_f32 v[98:99], v[16:17], v[68:69], v[98:99]
	s_cmp_lg_u32 s56, 3
	s_cbranch_scc1 .LBB0_1742
;   __device__ __forceinline__ half_t* mm() const { return (half_t*)(ws() + OFF_mm); }
; __device__ __forceinline__ void phase_merge(const KP& p, char* smem, int* q, int xcc) {
;     ...
; #pragma unroll
;     for (int mi = 0; mi < 2; ++mi)
; #pragma unroll
;       for (int ni = 0; ni < 2; ++ni)
; #pragma unroll
;         for (int r = 0; r < 16; ++r) {
;           const int row = wm * 64 + mi * 32 + (r & 3) + 8 * (r >> 2) + 4 * (lane >> 5);
;           const int col = wn * 64 + ni * 32 + (lane & 31);
;           p.mm()[(size_t)(m0 + row) * DM + n0 + col] = (half_t)tot[mi][ni][r];
;         }
	v_mov_b32_e32 v0, v224
	v_ashrrev_i32_e32 v2, 1, v0
	v_and_b32_e32 v2, 0xffffffc0, v2
	v_lshrrev_b32_e32 v3, 3, v0
	v_add_u32_e32 v2, s14, v2
	v_and_or_b32 v2, v3, 4, v2
	v_and_b32_e32 v3, 31, v0
	v_bfe_u32 v4, v0, 6, 1
	v_lshlrev_b32_e32 v3, 1, v3
	v_lshl_or_b32 v3, v4, 21, v3
	v_lshl_add_u32 v4, v2, 6, v3
	s_lshr_b32 s2, s18, 6
	s_lshl_b32 s2, s2, 20
	s_add_u32 s2, s44, s2
	s_addc_u32 s3, s45, 0
	s_add_u32 s40, s2, 0x100000
	s_addc_u32 s41, s3, 0
	v_cvt_f16_f32_e32 v5, v160
	global_store_short v4, v5, s[2:3]
	v_cvt_f16_f32_e32 v6, v161
	global_store_short v4, v6, s[2:3] offset:64
	v_cvt_f16_f32_e32 v7, v158
	global_store_short v4, v7, s[2:3] offset:128
	v_cvt_f16_f32_e32 v8, v159
	global_store_short v4, v8, s[2:3] offset:192
	v_cvt_f16_f32_e32 v9, v156
	global_store_short v4, v9, s[2:3] offset:512
	v_cvt_f16_f32_e32 v10, v157
	global_store_short v4, v10, s[2:3] offset:576
	v_cvt_f16_f32_e32 v11, v154
	global_store_short v4, v11, s[2:3] offset:640
	v_cvt_f16_f32_e32 v12, v155
	global_store_short v4, v12, s[2:3] offset:704
	v_cvt_f16_f32_e32 v5, v152
	global_store_short v4, v5, s[2:3] offset:1024
	v_cvt_f16_f32_e32 v6, v153
	global_store_short v4, v6, s[2:3] offset:1088
	v_cvt_f16_f32_e32 v7, v150
	global_store_short v4, v7, s[2:3] offset:1152
	v_cvt_f16_f32_e32 v8, v151
	global_store_short v4, v8, s[2:3] offset:1216
	v_cvt_f16_f32_e32 v9, v148
	global_store_short v4, v9, s[2:3] offset:1536
	v_cvt_f16_f32_e32 v10, v149
	global_store_short v4, v10, s[2:3] offset:1600
	v_cvt_f16_f32_e32 v11, v146
	global_store_short v4, v11, s[2:3] offset:1664
	v_cvt_f16_f32_e32 v12, v147
	global_store_short v4, v12, s[2:3] offset:1728
	v_cvt_f16_f32_e32 v5, v144
	global_store_short v4, v5, s[40:41]
	v_cvt_f16_f32_e32 v6, v145
	global_store_short v4, v6, s[40:41] offset:64
	v_cvt_f16_f32_e32 v7, v142
	global_store_short v4, v7, s[40:41] offset:128
	v_cvt_f16_f32_e32 v8, v143
	global_store_short v4, v8, s[40:41] offset:192
	v_cvt_f16_f32_e32 v9, v140
	global_store_short v4, v9, s[40:41] offset:512
	v_cvt_f16_f32_e32 v10, v141
	global_store_short v4, v10, s[40:41] offset:576
	v_cvt_f16_f32_e32 v11, v138
	global_store_short v4, v11, s[40:41] offset:640
	v_cvt_f16_f32_e32 v12, v139
	global_store_short v4, v12, s[40:41] offset:704
	v_cvt_f16_f32_e32 v5, v136
	global_store_short v4, v5, s[40:41] offset:1024
	v_cvt_f16_f32_e32 v6, v137
	global_store_short v4, v6, s[40:41] offset:1088
	v_cvt_f16_f32_e32 v7, v134
	global_store_short v4, v7, s[40:41] offset:1152
	v_cvt_f16_f32_e32 v8, v135
	global_store_short v4, v8, s[40:41] offset:1216
	v_cvt_f16_f32_e32 v9, v132
	global_store_short v4, v9, s[40:41] offset:1536
	v_cvt_f16_f32_e32 v10, v133
	global_store_short v4, v10, s[40:41] offset:1600
	v_cvt_f16_f32_e32 v11, v130
	global_store_short v4, v11, s[40:41] offset:1664
	v_cvt_f16_f32_e32 v12, v131
	global_store_short v4, v12, s[40:41] offset:1728
	v_cvt_f16_f32_e32 v5, v128
	global_store_short v4, v5, s[2:3] offset:2048
	v_cvt_f16_f32_e32 v6, v129
	global_store_short v4, v6, s[2:3] offset:2112
	v_cvt_f16_f32_e32 v7, v126
	global_store_short v4, v7, s[2:3] offset:2176
	v_cvt_f16_f32_e32 v8, v127
	global_store_short v4, v8, s[2:3] offset:2240
	v_cvt_f16_f32_e32 v9, v124
	global_store_short v4, v9, s[2:3] offset:2560
	v_cvt_f16_f32_e32 v10, v125
	global_store_short v4, v10, s[2:3] offset:2624
	v_cvt_f16_f32_e32 v11, v122
	global_store_short v4, v11, s[2:3] offset:2688
	v_cvt_f16_f32_e32 v12, v123
	global_store_short v4, v12, s[2:3] offset:2752
	v_cvt_f16_f32_e32 v5, v120
	global_store_short v4, v5, s[2:3] offset:3072
	v_cvt_f16_f32_e32 v6, v121
	global_store_short v4, v6, s[2:3] offset:3136
	v_cvt_f16_f32_e32 v7, v118
	global_store_short v4, v7, s[2:3] offset:3200
	v_cvt_f16_f32_e32 v8, v119
	global_store_short v4, v8, s[2:3] offset:3264
	v_cvt_f16_f32_e32 v9, v116
	global_store_short v4, v9, s[2:3] offset:3584
	v_cvt_f16_f32_e32 v10, v117
	global_store_short v4, v10, s[2:3] offset:3648
	v_cvt_f16_f32_e32 v11, v114
	global_store_short v4, v11, s[2:3] offset:3712
	v_cvt_f16_f32_e32 v12, v115
	global_store_short v4, v12, s[2:3] offset:3776
	v_cvt_f16_f32_e32 v5, v112
	global_store_short v4, v5, s[40:41] offset:2048
	v_cvt_f16_f32_e32 v6, v113
	global_store_short v4, v6, s[40:41] offset:2112
	v_cvt_f16_f32_e32 v7, v110
	global_store_short v4, v7, s[40:41] offset:2176
	v_cvt_f16_f32_e32 v8, v111
	global_store_short v4, v8, s[40:41] offset:2240
	v_cvt_f16_f32_e32 v9, v108
	global_store_short v4, v9, s[40:41] offset:2560
	v_cvt_f16_f32_e32 v10, v109
	global_store_short v4, v10, s[40:41] offset:2624
	v_cvt_f16_f32_e32 v11, v106
	global_store_short v4, v11, s[40:41] offset:2688
	v_cvt_f16_f32_e32 v12, v107
	global_store_short v4, v12, s[40:41] offset:2752
	v_cvt_f16_f32_e32 v5, v104
	global_store_short v4, v5, s[40:41] offset:3072
	v_cvt_f16_f32_e32 v6, v105
	global_store_short v4, v6, s[40:41] offset:3136
	v_cvt_f16_f32_e32 v7, v102
	global_store_short v4, v7, s[40:41] offset:3200
	v_cvt_f16_f32_e32 v8, v103
	global_store_short v4, v8, s[40:41] offset:3264
	v_cvt_f16_f32_e32 v9, v100
	global_store_short v4, v9, s[40:41] offset:3584
	v_cvt_f16_f32_e32 v10, v101
	global_store_short v4, v10, s[40:41] offset:3648
	v_cvt_f16_f32_e32 v11, v98
	global_store_short v4, v11, s[40:41] offset:3712
	v_cvt_f16_f32_e32 v12, v99
	global_store_short v4, v12, s[40:41] offset:3776
	s_branch .LBB0_1731

;   __device__ __forceinline__ const float* x() const { return (const float*)(const __attribute__((address_space(1))) float*)kp[0]; }
;   __device__ __forceinline__ half_t* woT() const { return (half_t*)(ws() + OFF_woT); }
;   __device__ __forceinline__ half_t* mm() const { return (half_t*)(ws() + OFF_mm); }
; template <class LA, class LB, class EP>
; __device__ __forceinline__ void gemm_tile_big(int K, LA loadA, LB loadB, EP epi, char* smem) {
;   half_t* sA = (half_t*)smem;
;   half_t* sB = sA + 256 * 72;
;   int tid = threadIdx.x;
;   asm volatile("" : "+v"(tid));
;   const int lane = tid & 63, wid = tid >> 6;
;   const int wm = wid >> 1, wn = wid & 1;
;   f32x16 acc[4][2];
; #pragma unroll
;   for (int i = 0; i < 4; ++i)
; #pragma unroll
;     for (int j = 0; j < 2; ++j)
; #pragma unroll
;       for (int r = 0; r < 16; ++r) acc[i][j][r] = 0.f;
;   const int lr = tid >> 3, lc = (tid & 7) * 8;
;   uint4 ra[8], rb[4];
; #pragma unroll
;   for (int i = 0; i < 8; ++i) ra[i] = loadA(lr + 32 * i, lc);
; #pragma unroll
;   for (int i = 0; i < 4; ++i) rb[i] = loadB(lr + 32 * i, lc);
;   const int nk = K >> 6;
;   for (int kt = 0; kt < nk; ++kt) {
;     __syncthreads();
; #pragma unroll
;     for (int i = 0; i < 8; ++i) *(uint4*)&sA[(lr + 32 * i) * 72 + lc] = ra[i];
; #pragma unroll
;     for (int i = 0; i < 4; ++i) *(uint4*)&sB[(lr + 32 * i) * 72 + lc] = rb[i];
;     __syncthreads();
; __device__ __forceinline__ void phase_outproj(const KP& p, char* smem, int* q, int xcc) {
;     ...
;     const int mt = grp * 8 + (within & 7), nt = (within >> 3);
;     const int m0 = mt * 256, n0 = nt * 128;
;     const half_t* A = p.mm() + (size_t)m0 * DM;
;     const half_t* B = p.woT() + (size_t)n0 * DM;
;     gemm_tile_big(
;         DM, [&](int r, int k) { return *(const uint4*)(A + (size_t)r * DM + k); },
;         [&](int r, int k) { return *(const uint4*)(B + (size_t)r * DM + k); },
.LBB0_1815:
	s_lshl_b32 s2, s14, 6
	s_sub_i32 s2, s15, s2
	s_lshl_b32 s15, s2, 8
	s_lshl_b32 s3, s38, 11
	s_and_b32 s15, s15, 0x700
	s_or_b32 s40, s3, s15
	s_lshl_b32 s2, s2, 4
	s_ashr_i32 s41, s40, 31
	v_mov_b32_e32 v193, v224
	s_and_b32 s38, s2, 0xffffff80
	s_lshl_b64 s[2:3], s[40:41], 11
	v_mov_b32_e32 v2, 0
	v_mov_b32_e32 v3, v2
	v_mov_b32_e32 v4, v2
	v_mov_b32_e32 v5, v2
	v_mov_b32_e32 v6, v2
	v_mov_b32_e32 v7, v2
	v_mov_b32_e32 v8, v2
	v_mov_b32_e32 v9, v2
	v_mov_b32_e32 v10, v2
	v_mov_b32_e32 v11, v2
	v_mov_b32_e32 v12, v2
	v_mov_b32_e32 v13, v2
	v_mov_b32_e32 v14, v2
	v_mov_b32_e32 v15, v2
	v_mov_b32_e32 v16, v2
	v_mov_b32_e32 v17, v2
	v_mov_b32_e32 v18, v2
	v_mov_b32_e32 v19, v2
	v_mov_b32_e32 v20, v2
	v_mov_b32_e32 v21, v2
	v_mov_b32_e32 v22, v2
	v_mov_b32_e32 v23, v2
	v_mov_b32_e32 v24, v2
	v_mov_b32_e32 v25, v2
	v_mov_b32_e32 v26, v2
	v_mov_b32_e32 v27, v2
	v_mov_b32_e32 v28, v2
	v_mov_b32_e32 v29, v2
	v_mov_b32_e32 v30, v2
	v_mov_b32_e32 v31, v2
	v_mov_b32_e32 v32, v2
	v_mov_b32_e32 v33, v2
	v_mov_b32_e32 v34, v2
	v_mov_b32_e32 v35, v2
	v_mov_b32_e32 v36, v2
	v_mov_b32_e32 v37, v2
	v_mov_b32_e32 v38, v2
	v_mov_b32_e32 v39, v2
	v_mov_b32_e32 v40, v2
	v_mov_b32_e32 v41, v2
	v_mov_b32_e32 v42, v2
	v_mov_b32_e32 v43, v2
	v_mov_b32_e32 v44, v2
	v_mov_b32_e32 v45, v2
	v_mov_b32_e32 v46, v2
	v_mov_b32_e32 v47, v2
	v_mov_b32_e32 v48, v2
	v_mov_b32_e32 v49, v2
	v_mov_b32_e32 v50, v2
	v_mov_b32_e32 v51, v2
	v_mov_b32_e32 v52, v2
	v_mov_b32_e32 v53, v2
	v_mov_b32_e32 v54, v2
	v_mov_b32_e32 v55, v2
	v_mov_b32_e32 v56, v2
	v_mov_b32_e32 v57, v2
	v_mov_b32_e32 v58, v2
	v_mov_b32_e32 v59, v2
	v_mov_b32_e32 v60, v2
	v_mov_b32_e32 v61, v2
	v_mov_b32_e32 v62, v2
	v_mov_b32_e32 v63, v2
	v_mov_b32_e32 v64, v2
	v_mov_b32_e32 v65, v2
	v_mov_b32_e32 v66, v2
	v_mov_b32_e32 v67, v2
	v_mov_b32_e32 v68, v2
	v_mov_b32_e32 v69, v2
	v_mov_b32_e32 v70, v2
	v_mov_b32_e32 v71, v2
	v_mov_b32_e32 v72, v2
	v_mov_b32_e32 v73, v2
	v_mov_b32_e32 v74, v2
	v_mov_b32_e32 v75, v2
	v_mov_b32_e32 v76, v2
	v_mov_b32_e32 v77, v2
	v_mov_b32_e32 v78, v2
	v_mov_b32_e32 v79, v2
	v_mov_b32_e32 v80, v2
	v_mov_b32_e32 v81, v2
	v_mov_b32_e32 v82, v2
	v_mov_b32_e32 v83, v2
	v_mov_b32_e32 v84, v2
	v_mov_b32_e32 v85, v2
	v_mov_b32_e32 v86, v2
	v_mov_b32_e32 v87, v2
	v_mov_b32_e32 v88, v2
	v_mov_b32_e32 v89, v2
	v_mov_b32_e32 v90, v2
	v_mov_b32_e32 v91, v2
	v_mov_b32_e32 v92, v2
	v_mov_b32_e32 v93, v2
	v_mov_b32_e32 v94, v2
	v_mov_b32_e32 v95, v2
	v_mov_b32_e32 v96, v2
	v_mov_b32_e32 v97, v2
	v_mov_b32_e32 v98, v2
	v_mov_b32_e32 v99, v2
	v_mov_b32_e32 v100, v2
	v_mov_b32_e32 v101, v2
	v_mov_b32_e32 v102, v2
	v_mov_b32_e32 v103, v2
	v_mov_b32_e32 v104, v2
	v_mov_b32_e32 v105, v2
	v_mov_b32_e32 v106, v2
	v_mov_b32_e32 v107, v2
	v_mov_b32_e32 v108, v2
	v_mov_b32_e32 v109, v2
	v_mov_b32_e32 v110, v2
	v_mov_b32_e32 v111, v2
	v_mov_b32_e32 v112, v2
	v_mov_b32_e32 v113, v2
	v_mov_b32_e32 v114, v2
	v_mov_b32_e32 v115, v2
	v_mov_b32_e32 v116, v2
	v_mov_b32_e32 v117, v2
	v_mov_b32_e32 v118, v2
	v_mov_b32_e32 v119, v2
	v_mov_b32_e32 v120, v2
	v_mov_b32_e32 v121, v2
	v_mov_b32_e32 v122, v2
	v_mov_b32_e32 v123, v2
	v_mov_b32_e32 v124, v2
	v_mov_b32_e32 v125, v2
	v_mov_b32_e32 v126, v2
	v_mov_b32_e32 v127, v2
	v_mov_b32_e32 v128, v2
	v_mov_b32_e32 v129, v2
	v_lshrrev_b32_e32 v208, 2, v224
	v_and_b32_e32 v209, 3, v224
	v_lshlrev_b32_e32 v210, 11, v208
	v_mul_u32_u24_e32 v196, 0x50, v208
	v_lshl_add_u32 v196, v209, 4, v196
	v_lshlrev_b32_e32 v208, 4, v224
	v_add_u32_e32 v209, 0x1000, v208
	v_add_u32_e32 v210, 0x2000, v208
	v_add_u32_e32 v211, 0x3000, v208
	v_lshrrev_b32_e32 v178, 7, v224
	v_and_b32_e32 v179, 31, v224
	v_lshl_or_b32 v178, v178, 7, v179
	v_mul_u32_u24_e32 v178, 0x50, v178
	v_bfe_u32 v212, v224, 5, 1
	v_lshl_add_u32 v178, v212, 4, v178
	v_bfe_u32 v213, v224, 6, 1
	v_lshl_or_b32 v179, v213, 6, v179
	v_mul_u32_u24_e32 v179, 0x50, v179
	v_lshl_add_u32 v179, v212, 4, v179
	s_lshl_b64 s[2:3], s[40:41], 6
	s_add_u32 s52, s44, s2
	s_addc_u32 s53, s45, s3
	s_ashr_i32 s39, s38, 31
	s_lshl_b64 s[2:3], s[38:39], 6
	s_add_u32 s42, s46, s2
	s_addc_u32 s43, s47, s3
	global_load_dwordx4 v[130:133], v208, s[52:53]
	global_load_dwordx4 v[134:137], v209, s[52:53]
	global_load_dwordx4 v[138:141], v210, s[52:53]
	global_load_dwordx4 v[142:145], v211, s[52:53]
	global_load_dwordx4 v[146:149], v208, s[42:43]
	global_load_dwordx4 v[150:153], v209, s[42:43]
	s_add_u32 s52, s52, 0x100000
	s_addc_u32 s53, s53, 0
	s_add_u32 s42, s42, 0x10000
	s_addc_u32 s43, s43, 0
	global_load_dwordx4 v[154:157], v208, s[52:53]
	global_load_dwordx4 v[158:161], v209, s[52:53]
	global_load_dwordx4 v[162:165], v210, s[52:53]
	global_load_dwordx4 v[166:169], v211, s[52:53]
	global_load_dwordx4 v[170:173], v208, s[42:43]
	global_load_dwordx4 v[174:177], v209, s[42:43]
	s_add_u32 s52, s52, 0x100000
	s_addc_u32 s53, s53, 0
	s_add_u32 s42, s42, 0x10000
	s_addc_u32 s43, s43, 0
	s_barrier
	s_waitcnt vmcnt(11)
	ds_write_b128 v196, v[130:133]
	s_waitcnt vmcnt(10)
	ds_write_b128 v196, v[134:137] offset:5120
	s_waitcnt vmcnt(9)
	ds_write_b128 v196, v[138:141] offset:10240
	s_waitcnt vmcnt(8)
	ds_write_b128 v196, v[142:145] offset:15360
	s_waitcnt vmcnt(7)
	ds_write_b128 v196, v[146:149] offset:20480
	s_waitcnt vmcnt(6)
	ds_write_b128 v196, v[150:153] offset:25600
	s_waitcnt lgkmcnt(0)
	s_barrier
	s_mov_b32 s15, 0
; template <class LA, class LB, class EP>
; __device__ __forceinline__ void gemm_tile_big(int K, LA loadA, LB loadB, EP epi, char* smem) {
;     ...
;   for (int kt = 0; kt < nk; ++kt) {
;     __syncthreads();
; #pragma unroll
;     for (int i = 0; i < 8; ++i) *(uint4*)&sA[(lr + 32 * i) * 72 + lc] = ra[i];
; #pragma unroll
;     for (int i = 0; i < 4; ++i) *(uint4*)&sB[(lr + 32 * i) * 72 + lc] = rb[i];
;     __syncthreads();
;     if (kt + 1 < nk) {
;       const int kk = (kt + 1) * 64 + lc;
; #pragma unroll
;       for (int i = 0; i < 8; ++i) ra[i] = loadA(lr + 32 * i, kk);
; #pragma unroll
;       for (int i = 0; i < 4; ++i) rb[i] = loadB(lr + 32 * i, kk);
;     }
; #pragma unroll
;     for (int s = 0; s < 4; ++s) {
;       h8 af[4], bf[2];
; #pragma unroll
;       for (int mi = 0; mi < 4; ++mi)
;         af[mi] = *(const h8*)&sA[(wm * 128 + mi * 32 + (lane & 31)) * 72 + s * 16 + (lane >> 5) * 8];
; #pragma unroll
;       for (int ni = 0; ni < 2; ++ni)
;         bf[ni] = *(const h8*)&sB[(wn * 64 + ni * 32 + (lane & 31)) * 72 + s * 16 + (lane >> 5) * 8];
; #pragma unroll
;       for (int mi = 0; mi < 4; ++mi)
; #pragma unroll
;         for (int ni = 0; ni < 2; ++ni)
;           acc[mi][ni] = __builtin_amdgcn_mfma_f32_32x32x16_f16(af[mi], bf[ni], acc[mi][ni], 0, 0, 0);
;     }
.Lgp2_loop:
	ds_read_b128 v[238:241], v179 offset:20480
	ds_read_b128 v[242:245], v179 offset:23040
	ds_read_b128 v[200:203], v178
	ds_read_b128 v[204:207], v178 offset:2560
	ds_read_b128 v[214:217], v178 offset:5120
	ds_read_b128 v[218:221], v178 offset:7680
	global_load_dwordx4 v[130:133], v208, s[52:53]
	global_load_dwordx4 v[134:137], v209, s[52:53]
	global_load_dwordx4 v[138:141], v210, s[52:53]
	global_load_dwordx4 v[142:145], v211, s[52:53]
	global_load_dwordx4 v[146:149], v208, s[42:43]
	global_load_dwordx4 v[150:153], v209, s[42:43]
	s_add_u32 s52, s52, 0x100000
	s_addc_u32 s53, s53, 0
	s_add_u32 s42, s42, 0x10000
	s_addc_u32 s43, s43, 0
	ds_read_b128 v[226:229], v179 offset:20512
	ds_read_b128 v[230:233], v179 offset:23072
	s_waitcnt lgkmcnt(5)
	v_mfma_f32_32x32x16_f16 v[114:129], v[200:203], v[238:241], v[114:129]
	v_mfma_f32_32x32x16_f16 v[98:113], v[200:203], v[242:245], v[98:113]
	ds_read_b128 v[200:203], v178 offset:32
	s_waitcnt lgkmcnt(5)
	v_mfma_f32_32x32x16_f16 v[82:97], v[204:207], v[238:241], v[82:97]
	v_mfma_f32_32x32x16_f16 v[66:81], v[204:207], v[242:245], v[66:81]
	ds_read_b128 v[204:207], v178 offset:2592
	s_waitcnt vmcnt(11)
	ds_write_b128 v196, v[154:157] offset:30720
	s_waitcnt lgkmcnt(6)
	v_mfma_f32_32x32x16_f16 v[50:65], v[214:217], v[238:241], v[50:65]
	v_mfma_f32_32x32x16_f16 v[34:49], v[214:217], v[242:245], v[34:49]
	ds_read_b128 v[214:217], v178 offset:5152
	s_waitcnt vmcnt(10)
	ds_write_b128 v196, v[158:161] offset:35840
	s_waitcnt lgkmcnt(7)
	v_mfma_f32_32x32x16_f16 v[18:33], v[218:221], v[238:241], v[18:33]
	v_mfma_f32_32x32x16_f16 v[2:17], v[218:221], v[242:245], v[2:17]
	ds_read_b128 v[218:221], v178 offset:7712
	s_waitcnt vmcnt(9)
	ds_write_b128 v196, v[162:165] offset:40960
	s_waitcnt lgkmcnt(6)
	v_mfma_f32_32x32x16_f16 v[114:129], v[200:203], v[226:229], v[114:129]
	v_mfma_f32_32x32x16_f16 v[98:113], v[200:203], v[230:233], v[98:113]
	s_waitcnt vmcnt(8)
	ds_write_b128 v196, v[166:169] offset:46080
	s_waitcnt lgkmcnt(6)
	v_mfma_f32_32x32x16_f16 v[82:97], v[204:207], v[226:229], v[82:97]
	v_mfma_f32_32x32x16_f16 v[66:81], v[204:207], v[230:233], v[66:81]
	s_waitcnt vmcnt(7)
	ds_write_b128 v196, v[170:173] offset:51200
	s_waitcnt lgkmcnt(5)
	v_mfma_f32_32x32x16_f16 v[50:65], v[214:217], v[226:229], v[50:65]
	v_mfma_f32_32x32x16_f16 v[34:49], v[214:217], v[230:233], v[34:49]
	s_waitcnt vmcnt(6)
	ds_write_b128 v196, v[174:177] offset:56320
	s_waitcnt lgkmcnt(4)
	v_mfma_f32_32x32x16_f16 v[18:33], v[218:221], v[226:229], v[18:33]
	v_mfma_f32_32x32x16_f16 v[2:17], v[218:221], v[230:233], v[2:17]
	s_waitcnt lgkmcnt(0)
	s_barrier
	ds_read_b128 v[238:241], v179 offset:51200
	ds_read_b128 v[242:245], v179 offset:53760
	ds_read_b128 v[200:203], v178 offset:30720
	ds_read_b128 v[204:207], v178 offset:33280
	ds_read_b128 v[214:217], v178 offset:35840
	ds_read_b128 v[218:221], v178 offset:38400
	global_load_dwordx4 v[154:157], v208, s[52:53]
	global_load_dwordx4 v[158:161], v209, s[52:53]
	global_load_dwordx4 v[162:165], v210, s[52:53]
	global_load_dwordx4 v[166:169], v211, s[52:53]
	global_load_dwordx4 v[170:173], v208, s[42:43]
	global_load_dwordx4 v[174:177], v209, s[42:43]
	s_add_u32 s52, s52, 0x100000
	s_addc_u32 s53, s53, 0
	s_add_u32 s42, s42, 0x10000
	s_addc_u32 s43, s43, 0
	ds_read_b128 v[226:229], v179 offset:51232
	ds_read_b128 v[230:233], v179 offset:53792
	s_waitcnt lgkmcnt(5)
	v_mfma_f32_32x32x16_f16 v[114:129], v[200:203], v[238:241], v[114:129]
	v_mfma_f32_32x32x16_f16 v[98:113], v[200:203], v[242:245], v[98:113]
	ds_read_b128 v[200:203], v178 offset:30752
	s_waitcnt lgkmcnt(5)
	v_mfma_f32_32x32x16_f16 v[82:97], v[204:207], v[238:241], v[82:97]
	v_mfma_f32_32x32x16_f16 v[66:81], v[204:207], v[242:245], v[66:81]
	ds_read_b128 v[204:207], v178 offset:33312
	s_waitcnt vmcnt(11)
	ds_write_b128 v196, v[130:133]
	s_waitcnt lgkmcnt(6)
	v_mfma_f32_32x32x16_f16 v[50:65], v[214:217], v[238:241], v[50:65]
	v_mfma_f32_32x32x16_f16 v[34:49], v[214:217], v[242:245], v[34:49]
	ds_read_b128 v[214:217], v178 offset:35872
	s_waitcnt vmcnt(10)
	ds_write_b128 v196, v[134:137] offset:5120
	s_waitcnt lgkmcnt(7)
	v_mfma_f32_32x32x16_f16 v[18:33], v[218:221], v[238:241], v[18:33]
	v_mfma_f32_32x32x16_f16 v[2:17], v[218:221], v[242:245], v[2:17]
	ds_read_b128 v[218:221], v178 offset:38432
	s_waitcnt vmcnt(9)
	ds_write_b128 v196, v[138:141] offset:10240
	s_waitcnt lgkmcnt(6)
	v_mfma_f32_32x32x16_f16 v[114:129], v[200:203], v[226:229], v[114:129]
	v_mfma_f32_32x32x16_f16 v[98:113], v[200:203], v[230:233], v[98:113]
	s_waitcnt vmcnt(8)
	ds_write_b128 v196, v[142:145] offset:15360
	s_waitcnt lgkmcnt(6)
	v_mfma_f32_32x32x16_f16 v[82:97], v[204:207], v[226:229], v[82:97]
	v_mfma_f32_32x32x16_f16 v[66:81], v[204:207], v[230:233], v[66:81]
	s_waitcnt vmcnt(7)
	ds_write_b128 v196, v[146:149] offset:20480
	s_waitcnt lgkmcnt(5)
	v_mfma_f32_32x32x16_f16 v[50:65], v[214:217], v[226:229], v[50:65]
	v_mfma_f32_32x32x16_f16 v[34:49], v[214:217], v[230:233], v[34:49]
	s_waitcnt vmcnt(6)
	ds_write_b128 v196, v[150:153] offset:25600
	s_waitcnt lgkmcnt(4)
	v_mfma_f32_32x32x16_f16 v[18:33], v[218:221], v[226:229], v[18:33]
	v_mfma_f32_32x32x16_f16 v[2:17], v[218:221], v[230:233], v[2:17]
	s_waitcnt lgkmcnt(0)
	s_barrier
	s_add_i32 s15, s15, 1
	s_cmp_lt_u32 s15, 15
	s_cbranch_scc1 .Lgp2_loop
;   __device__ __forceinline__ float* xr() const { return (float*)(ws() + OFF_xr); }
;   __device__ __forceinline__ half_t* u() const { return (half_t*)(ws() + OFF_u); }
; template <class LA, class LB, class EP>
; __device__ __forceinline__ void gemm_tile_big(int K, LA loadA, LB loadB, EP epi, char* smem) {
;     ...
;     for (int s = 0; s < 4; ++s) {
;       h8 af[4], bf[2];
; #pragma unroll
;       for (int mi = 0; mi < 4; ++mi)
;         af[mi] = *(const h8*)&sA[(wm * 128 + mi * 32 + (lane & 31)) * 72 + s * 16 + (lane >> 5) * 8];
; #pragma unroll
;       for (int ni = 0; ni < 2; ++ni)
;         bf[ni] = *(const h8*)&sB[(wn * 64 + ni * 32 + (lane & 31)) * 72 + s * 16 + (lane >> 5) * 8];
; #pragma unroll
;       for (int mi = 0; mi < 4; ++mi)
; #pragma unroll
;         for (int ni = 0; ni < 2; ++ni)
;           acc[mi][ni] = __builtin_amdgcn_mfma_f32_32x32x16_f16(af[mi], bf[ni], acc[mi][ni], 0, 0, 0);
;     }
; __device__ __forceinline__ void phase_outproj(const KP& p, char* smem, int* q, int xcc) {
;     ...
;         [&](int mi, int ni, int r, int row, int col, float v) {
;           const size_t xi = (size_t)(m0 + row) * DM + n0 + col;
;           ((float*)p.u())[xi] = ALPHA_F * p.xr()[xi] + v;
;         },
	ds_read_b128 v[238:241], v179 offset:20480
	ds_read_b128 v[242:245], v179 offset:23040
	ds_read_b128 v[200:203], v178
	ds_read_b128 v[204:207], v178 offset:2560
	ds_read_b128 v[214:217], v178 offset:5120
	ds_read_b128 v[218:221], v178 offset:7680
	ds_read_b128 v[226:229], v179 offset:20512
	ds_read_b128 v[230:233], v179 offset:23072
	s_waitcnt lgkmcnt(5)
	v_mfma_f32_32x32x16_f16 v[114:129], v[200:203], v[238:241], v[114:129]
	v_mfma_f32_32x32x16_f16 v[98:113], v[200:203], v[242:245], v[98:113]
	ds_read_b128 v[200:203], v178 offset:32
	s_waitcnt lgkmcnt(5)
	v_mfma_f32_32x32x16_f16 v[82:97], v[204:207], v[238:241], v[82:97]
	v_mfma_f32_32x32x16_f16 v[66:81], v[204:207], v[242:245], v[66:81]
	ds_read_b128 v[204:207], v178 offset:2592
	s_waitcnt vmcnt(5)
	ds_write_b128 v196, v[154:157] offset:30720
	s_waitcnt lgkmcnt(6)
	v_mfma_f32_32x32x16_f16 v[50:65], v[214:217], v[238:241], v[50:65]
	v_mfma_f32_32x32x16_f16 v[34:49], v[214:217], v[242:245], v[34:49]
	ds_read_b128 v[214:217], v178 offset:5152
	s_waitcnt vmcnt(4)
	ds_write_b128 v196, v[158:161] offset:35840
	s_waitcnt lgkmcnt(7)
	v_mfma_f32_32x32x16_f16 v[18:33], v[218:221], v[238:241], v[18:33]
	v_mfma_f32_32x32x16_f16 v[2:17], v[218:221], v[242:245], v[2:17]
	ds_read_b128 v[218:221], v178 offset:7712
	s_waitcnt vmcnt(3)
	ds_write_b128 v196, v[162:165] offset:40960
	s_waitcnt lgkmcnt(6)
	v_mfma_f32_32x32x16_f16 v[114:129], v[200:203], v[226:229], v[114:129]
	v_mfma_f32_32x32x16_f16 v[98:113], v[200:203], v[230:233], v[98:113]
	s_waitcnt vmcnt(2)
	ds_write_b128 v196, v[166:169] offset:46080
	s_waitcnt lgkmcnt(6)
	v_mfma_f32_32x32x16_f16 v[82:97], v[204:207], v[226:229], v[82:97]
	v_mfma_f32_32x32x16_f16 v[66:81], v[204:207], v[230:233], v[66:81]
	s_waitcnt vmcnt(1)
	ds_write_b128 v196, v[170:173] offset:51200
	s_waitcnt lgkmcnt(5)
	v_mfma_f32_32x32x16_f16 v[50:65], v[214:217], v[226:229], v[50:65]
	v_mfma_f32_32x32x16_f16 v[34:49], v[214:217], v[230:233], v[34:49]
	s_waitcnt vmcnt(0)
	ds_write_b128 v196, v[174:177] offset:56320
	s_waitcnt lgkmcnt(4)
	v_mfma_f32_32x32x16_f16 v[18:33], v[218:221], v[226:229], v[18:33]
	v_mfma_f32_32x32x16_f16 v[2:17], v[218:221], v[230:233], v[2:17]
	s_waitcnt lgkmcnt(0)
	s_barrier
	ds_read_b128 v[238:241], v179 offset:51200
	ds_read_b128 v[242:245], v179 offset:53760
	ds_read_b128 v[200:203], v178 offset:30720
	ds_read_b128 v[204:207], v178 offset:33280
	ds_read_b128 v[214:217], v178 offset:35840
	ds_read_b128 v[218:221], v178 offset:38400
	ds_read_b128 v[226:229], v179 offset:51232
	ds_read_b128 v[230:233], v179 offset:53792
	s_waitcnt lgkmcnt(5)
	v_mfma_f32_32x32x16_f16 v[114:129], v[200:203], v[238:241], v[114:129]
	v_mfma_f32_32x32x16_f16 v[98:113], v[200:203], v[242:245], v[98:113]
	ds_read_b128 v[200:203], v178 offset:30752
	s_waitcnt lgkmcnt(5)
	v_mfma_f32_32x32x16_f16 v[82:97], v[204:207], v[238:241], v[82:97]
	v_mfma_f32_32x32x16_f16 v[66:81], v[204:207], v[242:245], v[66:81]
	ds_read_b128 v[204:207], v178 offset:33312
	s_waitcnt lgkmcnt(5)
	v_mfma_f32_32x32x16_f16 v[50:65], v[214:217], v[238:241], v[50:65]
	v_mfma_f32_32x32x16_f16 v[34:49], v[214:217], v[242:245], v[34:49]
	ds_read_b128 v[214:217], v178 offset:35872
	s_waitcnt lgkmcnt(5)
	v_mfma_f32_32x32x16_f16 v[18:33], v[218:221], v[238:241], v[18:33]
	v_mfma_f32_32x32x16_f16 v[2:17], v[218:221], v[242:245], v[2:17]
	ds_read_b128 v[218:221], v178 offset:38432
	s_waitcnt lgkmcnt(3)
	v_mfma_f32_32x32x16_f16 v[114:129], v[200:203], v[226:229], v[114:129]
	v_mfma_f32_32x32x16_f16 v[98:113], v[200:203], v[230:233], v[98:113]
	s_waitcnt lgkmcnt(2)
	v_mfma_f32_32x32x16_f16 v[82:97], v[204:207], v[226:229], v[82:97]
	v_mfma_f32_32x32x16_f16 v[66:81], v[204:207], v[230:233], v[66:81]
	s_waitcnt lgkmcnt(1)
	v_mfma_f32_32x32x16_f16 v[50:65], v[214:217], v[226:229], v[50:65]
	v_mfma_f32_32x32x16_f16 v[34:49], v[214:217], v[230:233], v[34:49]
	s_waitcnt lgkmcnt(0)
	v_mfma_f32_32x32x16_f16 v[18:33], v[218:221], v[226:229], v[18:33]
	v_mfma_f32_32x32x16_f16 v[2:17], v[218:221], v[230:233], v[2:17]
	s_waitcnt lgkmcnt(0)
	v_mov_b32_e32 v226, 1
	v_mov_b32_e32 v227, 0x11fe0
	v_mov_b32_e32 v228, 0x11fe4
	v_mov_b32_e32 v229, 0x100
	v_mov_b32_e32 v230, 2
	v_mov_b32_e32 v231, 0x3727c5ac
	v_mov_b32_e32 v232, 0x11fa0
	v_mov_b32_e32 v233, 0x80000
	v_mov_b32_e32 v238, 0x4000
	v_mov_b32_e32 v239, 0x4400
	v_mov_b32_e32 v240, 0x4800
	v_mov_b32_e32 v241, 0x4c00
	v_mov_b32_e32 v242, 0xf149f2ca
	v_mov_b32_e32 v243, 0x200
	v_mov_b32_e32 v244, 0x400
	v_mov_b32_e32 v245, 0x600
	s_nop 15
	s_lshl_b32 s2, s40, 10
	s_add_u32 s2, s2, s38
	s_lshl_b32 s2, s2, 2
	s_add_u32 s52, s0, s2
	s_addc_u32 s53, s1, 0
	s_add_u32 s42, s10, s2
	s_addc_u32 s43, s11, 0
	v_lshrrev_b32_e32 v180, 7, v224
	v_lshlrev_b32_e32 v180, 19, v180
	v_bfe_u32 v181, v224, 5, 1
	v_lshl_or_b32 v180, v181, 14, v180
	v_bfe_u32 v181, v224, 6, 1
	v_lshl_or_b32 v180, v181, 8, v180
	v_and_b32_e32 v181, 31, v224
	v_lshl_or_b32 v180, v181, 2, v180
	s_add_u32 s2, s52, 0x0
	s_addc_u32 s3, s53, 0
	global_load_dword v130, v180, s[2:3]
	global_load_dword v131, v180, s[2:3] offset:128
	s_add_u32 s2, s52, 0x1000
	s_addc_u32 s3, s53, 0
	global_load_dword v132, v180, s[2:3]
	global_load_dword v133, v180, s[2:3] offset:128
	s_add_u32 s2, s52, 0x2000
	s_addc_u32 s3, s53, 0
	global_load_dword v134, v180, s[2:3]
	global_load_dword v135, v180, s[2:3] offset:128
	s_add_u32 s2, s52, 0x3000
	s_addc_u32 s3, s53, 0
	global_load_dword v136, v180, s[2:3]
	global_load_dword v137, v180, s[2:3] offset:128
	s_add_u32 s2, s52, 0x8000
	s_addc_u32 s3, s53, 0
	global_load_dword v138, v180, s[2:3]
	global_load_dword v139, v180, s[2:3] offset:128
	s_add_u32 s2, s52, 0x9000
	s_addc_u32 s3, s53, 0
;   __device__ __forceinline__ float* xr() const { return (float*)(ws() + OFF_xr); }
;   __device__ __forceinline__ half_t* u() const { return (half_t*)(ws() + OFF_u); }
; __device__ __forceinline__ void phase_outproj(const KP& p, char* smem, int* q, int xcc) {
;     ...
;         [&](int mi, int ni, int r, int row, int col, float v) {
;           const size_t xi = (size_t)(m0 + row) * DM + n0 + col;
;           ((float*)p.u())[xi] = ALPHA_F * p.xr()[xi] + v;
;         },
	global_load_dword v140, v180, s[2:3]
	global_load_dword v141, v180, s[2:3] offset:128
	s_add_u32 s2, s52, 0xa000
	s_addc_u32 s3, s53, 0
	global_load_dword v142, v180, s[2:3]
	global_load_dword v143, v180, s[2:3] offset:128
	s_add_u32 s2, s52, 0xb000
	s_addc_u32 s3, s53, 0
	global_load_dword v144, v180, s[2:3]
	global_load_dword v145, v180, s[2:3] offset:128
	s_add_u32 s2, s52, 0x10000
	s_addc_u32 s3, s53, 0
	global_load_dword v146, v180, s[2:3]
	global_load_dword v147, v180, s[2:3] offset:128
	s_add_u32 s2, s52, 0x11000
	s_addc_u32 s3, s53, 0
	global_load_dword v148, v180, s[2:3]
	global_load_dword v149, v180, s[2:3] offset:128
	s_add_u32 s2, s52, 0x12000
	s_addc_u32 s3, s53, 0
	global_load_dword v150, v180, s[2:3]
	global_load_dword v151, v180, s[2:3] offset:128
	s_add_u32 s2, s52, 0x13000
	s_addc_u32 s3, s53, 0
	global_load_dword v152, v180, s[2:3]
	global_load_dword v153, v180, s[2:3] offset:128
	s_add_u32 s2, s52, 0x18000
	s_addc_u32 s3, s53, 0
	global_load_dword v154, v180, s[2:3]
	global_load_dword v155, v180, s[2:3] offset:128
	s_add_u32 s2, s52, 0x19000
	s_addc_u32 s3, s53, 0
	global_load_dword v156, v180, s[2:3]
	global_load_dword v157, v180, s[2:3] offset:128
	s_add_u32 s2, s52, 0x1a000
	s_addc_u32 s3, s53, 0
	global_load_dword v158, v180, s[2:3]
	global_load_dword v159, v180, s[2:3] offset:128
	s_add_u32 s2, s52, 0x1b000
	s_addc_u32 s3, s53, 0
	global_load_dword v160, v180, s[2:3]
	global_load_dword v161, v180, s[2:3] offset:128
	s_add_u32 s2, s52, 0x20000
	s_addc_u32 s3, s53, 0
	global_load_dword v162, v180, s[2:3]
	global_load_dword v163, v180, s[2:3] offset:128
	s_add_u32 s2, s52, 0x21000
	s_addc_u32 s3, s53, 0
	global_load_dword v164, v180, s[2:3]
	global_load_dword v165, v180, s[2:3] offset:128
	s_add_u32 s2, s52, 0x22000
	s_addc_u32 s3, s53, 0
	global_load_dword v166, v180, s[2:3]
	global_load_dword v167, v180, s[2:3] offset:128
	s_add_u32 s2, s52, 0x23000
	s_addc_u32 s3, s53, 0
	global_load_dword v168, v180, s[2:3]
	global_load_dword v169, v180, s[2:3] offset:128
	s_add_u32 s2, s52, 0x28000
	s_addc_u32 s3, s53, 0
	global_load_dword v170, v180, s[2:3]
	global_load_dword v171, v180, s[2:3] offset:128
	s_add_u32 s2, s52, 0x29000
	s_addc_u32 s3, s53, 0
	global_load_dword v172, v180, s[2:3]
	global_load_dword v173, v180, s[2:3] offset:128
	s_add_u32 s2, s52, 0x2a000
	s_addc_u32 s3, s53, 0
	global_load_dword v174, v180, s[2:3]
	global_load_dword v175, v180, s[2:3] offset:128
	s_add_u32 s2, s52, 0x2b000
	s_addc_u32 s3, s53, 0
	global_load_dword v176, v180, s[2:3]
	global_load_dword v177, v180, s[2:3] offset:128
	s_waitcnt vmcnt(32)
	v_fmamk_f32 v114, v130, 0x3fd744fd, v114
	v_fmamk_f32 v98, v131, 0x3fd744fd, v98
	v_fmamk_f32 v115, v132, 0x3fd744fd, v115
	v_fmamk_f32 v99, v133, 0x3fd744fd, v99
	v_fmamk_f32 v116, v134, 0x3fd744fd, v116
	v_fmamk_f32 v100, v135, 0x3fd744fd, v100
	v_fmamk_f32 v117, v136, 0x3fd744fd, v117
	v_fmamk_f32 v101, v137, 0x3fd744fd, v101
	v_fmamk_f32 v118, v138, 0x3fd744fd, v118
	v_fmamk_f32 v102, v139, 0x3fd744fd, v102
	v_fmamk_f32 v119, v140, 0x3fd744fd, v119
	v_fmamk_f32 v103, v141, 0x3fd744fd, v103
	v_fmamk_f32 v120, v142, 0x3fd744fd, v120
	v_fmamk_f32 v104, v143, 0x3fd744fd, v104
	v_fmamk_f32 v121, v144, 0x3fd744fd, v121
	v_fmamk_f32 v105, v145, 0x3fd744fd, v105
	s_add_u32 s2, s52, 0x30000
	s_addc_u32 s3, s53, 0
	global_load_dword v130, v180, s[2:3]
	global_load_dword v131, v180, s[2:3] offset:128
	s_add_u32 s2, s52, 0x31000
	s_addc_u32 s3, s53, 0
	global_load_dword v132, v180, s[2:3]
	global_load_dword v133, v180, s[2:3] offset:128
	s_add_u32 s2, s52, 0x32000
	s_addc_u32 s3, s53, 0
	global_load_dword v134, v180, s[2:3]
	global_load_dword v135, v180, s[2:3] offset:128
	s_add_u32 s2, s52, 0x33000
	s_addc_u32 s3, s53, 0
	global_load_dword v136, v180, s[2:3]
	global_load_dword v137, v180, s[2:3] offset:128
	s_add_u32 s2, s52, 0x38000
	s_addc_u32 s3, s53, 0
	global_load_dword v138, v180, s[2:3]
	global_load_dword v139, v180, s[2:3] offset:128
	s_add_u32 s2, s52, 0x39000
	s_addc_u32 s3, s53, 0
	global_load_dword v140, v180, s[2:3]
	global_load_dword v141, v180, s[2:3] offset:128
	s_add_u32 s2, s52, 0x3a000
	s_addc_u32 s3, s53, 0
	global_load_dword v142, v180, s[2:3]
	global_load_dword v143, v180, s[2:3] offset:128
	s_add_u32 s2, s52, 0x3b000
	s_addc_u32 s3, s53, 0
	global_load_dword v144, v180, s[2:3]
	global_load_dword v145, v180, s[2:3] offset:128
	s_waitcnt vmcnt(32)
	v_fmamk_f32 v122, v146, 0x3fd744fd, v122
	v_fmamk_f32 v106, v147, 0x3fd744fd, v106
	v_fmamk_f32 v123, v148, 0x3fd744fd, v123
	v_fmamk_f32 v107, v149, 0x3fd744fd, v107
	v_fmamk_f32 v124, v150, 0x3fd744fd, v124
	v_fmamk_f32 v108, v151, 0x3fd744fd, v108
	v_fmamk_f32 v125, v152, 0x3fd744fd, v125
	v_fmamk_f32 v109, v153, 0x3fd744fd, v109
	v_fmamk_f32 v126, v154, 0x3fd744fd, v126
	v_fmamk_f32 v110, v155, 0x3fd744fd, v110
	v_fmamk_f32 v127, v156, 0x3fd744fd, v127
	v_fmamk_f32 v111, v157, 0x3fd744fd, v111
	v_fmamk_f32 v128, v158, 0x3fd744fd, v128
	v_fmamk_f32 v112, v159, 0x3fd744fd, v112
	v_fmamk_f32 v129, v160, 0x3fd744fd, v129
	v_fmamk_f32 v113, v161, 0x3fd744fd, v113
	s_add_u32 s2, s52, 0x40000
	s_addc_u32 s3, s53, 0
	global_load_dword v146, v180, s[2:3]
	global_load_dword v147, v180, s[2:3] offset:128
	s_add_u32 s2, s52, 0x41000
	s_addc_u32 s3, s53, 0
	global_load_dword v148, v180, s[2:3]
	global_load_dword v149, v180, s[2:3] offset:128
	s_add_u32 s2, s52, 0x42000
	s_addc_u32 s3, s53, 0
	global_load_dword v150, v180, s[2:3]
	global_load_dword v151, v180, s[2:3] offset:128
	s_add_u32 s2, s52, 0x43000
	s_addc_u32 s3, s53, 0
	global_load_dword v152, v180, s[2:3]
	global_load_dword v153, v180, s[2:3] offset:128
	s_add_u32 s2, s52, 0x48000
	s_addc_u32 s3, s53, 0
	global_load_dword v154, v180, s[2:3]
	global_load_dword v155, v180, s[2:3] offset:128
	s_add_u32 s2, s52, 0x49000
	s_addc_u32 s3, s53, 0
	global_load_dword v156, v180, s[2:3]
	global_load_dword v157, v180, s[2:3] offset:128
	s_add_u32 s2, s52, 0x4a000
	s_addc_u32 s3, s53, 0
	global_load_dword v158, v180, s[2:3]
	global_load_dword v159, v180, s[2:3] offset:128
	s_add_u32 s2, s52, 0x4b000
	s_addc_u32 s3, s53, 0
	global_load_dword v160, v180, s[2:3]
	global_load_dword v161, v180, s[2:3] offset:128
	s_waitcnt vmcnt(32)
;   __device__ __forceinline__ float* xr() const { return (float*)(ws() + OFF_xr); }
;   __device__ __forceinline__ half_t* u() const { return (half_t*)(ws() + OFF_u); }
; __device__ __forceinline__ void phase_outproj(const KP& p, char* smem, int* q, int xcc) {
;     ...
;         [&](int mi, int ni, int r, int row, int col, float v) {
;           const size_t xi = (size_t)(m0 + row) * DM + n0 + col;
;           ((float*)p.u())[xi] = ALPHA_F * p.xr()[xi] + v;
;         },
	v_fmamk_f32 v82, v162, 0x3fd744fd, v82
	v_fmamk_f32 v66, v163, 0x3fd744fd, v66
	v_fmamk_f32 v83, v164, 0x3fd744fd, v83
	v_fmamk_f32 v67, v165, 0x3fd744fd, v67
	v_fmamk_f32 v84, v166, 0x3fd744fd, v84
	v_fmamk_f32 v68, v167, 0x3fd744fd, v68
	v_fmamk_f32 v85, v168, 0x3fd744fd, v85
	v_fmamk_f32 v69, v169, 0x3fd744fd, v69
	v_fmamk_f32 v86, v170, 0x3fd744fd, v86
	v_fmamk_f32 v70, v171, 0x3fd744fd, v70
	v_fmamk_f32 v87, v172, 0x3fd744fd, v87
	v_fmamk_f32 v71, v173, 0x3fd744fd, v71
	v_fmamk_f32 v88, v174, 0x3fd744fd, v88
	v_fmamk_f32 v72, v175, 0x3fd744fd, v72
	v_fmamk_f32 v89, v176, 0x3fd744fd, v89
	v_fmamk_f32 v73, v177, 0x3fd744fd, v73
	s_add_u32 s2, s52, 0x50000
	s_addc_u32 s3, s53, 0
	global_load_dword v162, v180, s[2:3]
	global_load_dword v163, v180, s[2:3] offset:128
	s_add_u32 s2, s52, 0x51000
	s_addc_u32 s3, s53, 0
	global_load_dword v164, v180, s[2:3]
	global_load_dword v165, v180, s[2:3] offset:128
	s_add_u32 s2, s52, 0x52000
	s_addc_u32 s3, s53, 0
	global_load_dword v166, v180, s[2:3]
	global_load_dword v167, v180, s[2:3] offset:128
	s_add_u32 s2, s52, 0x53000
	s_addc_u32 s3, s53, 0
	global_load_dword v168, v180, s[2:3]
	global_load_dword v169, v180, s[2:3] offset:128
	s_add_u32 s2, s52, 0x58000
	s_addc_u32 s3, s53, 0
	global_load_dword v170, v180, s[2:3]
	global_load_dword v171, v180, s[2:3] offset:128
	s_add_u32 s2, s52, 0x59000
	s_addc_u32 s3, s53, 0
	global_load_dword v172, v180, s[2:3]
	global_load_dword v173, v180, s[2:3] offset:128
	s_add_u32 s2, s52, 0x5a000
	s_addc_u32 s3, s53, 0
	global_load_dword v174, v180, s[2:3]
	global_load_dword v175, v180, s[2:3] offset:128
	s_add_u32 s2, s52, 0x5b000
	s_addc_u32 s3, s53, 0
	global_load_dword v176, v180, s[2:3]
	global_load_dword v177, v180, s[2:3] offset:128
	s_waitcnt vmcnt(32)
	v_fmamk_f32 v90, v130, 0x3fd744fd, v90
	v_fmamk_f32 v74, v131, 0x3fd744fd, v74
	v_fmamk_f32 v91, v132, 0x3fd744fd, v91
	v_fmamk_f32 v75, v133, 0x3fd744fd, v75
	v_fmamk_f32 v92, v134, 0x3fd744fd, v92
	v_fmamk_f32 v76, v135, 0x3fd744fd, v76
	v_fmamk_f32 v93, v136, 0x3fd744fd, v93
	v_fmamk_f32 v77, v137, 0x3fd744fd, v77
	v_fmamk_f32 v94, v138, 0x3fd744fd, v94
	v_fmamk_f32 v78, v139, 0x3fd744fd, v78
	v_fmamk_f32 v95, v140, 0x3fd744fd, v95
	v_fmamk_f32 v79, v141, 0x3fd744fd, v79
	v_fmamk_f32 v96, v142, 0x3fd744fd, v96
	v_fmamk_f32 v80, v143, 0x3fd744fd, v80
	v_fmamk_f32 v97, v144, 0x3fd744fd, v97
	v_fmamk_f32 v81, v145, 0x3fd744fd, v81
	s_add_u32 s2, s52, 0x60000
	s_addc_u32 s3, s53, 0
	global_load_dword v130, v180, s[2:3]
	global_load_dword v131, v180, s[2:3] offset:128
	s_add_u32 s2, s52, 0x61000
	s_addc_u32 s3, s53, 0
	global_load_dword v132, v180, s[2:3]
	global_load_dword v133, v180, s[2:3] offset:128
	s_add_u32 s2, s52, 0x62000
	s_addc_u32 s3, s53, 0
	global_load_dword v134, v180, s[2:3]
	global_load_dword v135, v180, s[2:3] offset:128
	s_add_u32 s2, s52, 0x63000
	s_addc_u32 s3, s53, 0
	global_load_dword v136, v180, s[2:3]
	global_load_dword v137, v180, s[2:3] offset:128
	s_add_u32 s2, s52, 0x68000
	s_addc_u32 s3, s53, 0
	global_load_dword v138, v180, s[2:3]
	global_load_dword v139, v180, s[2:3] offset:128
	s_add_u32 s2, s52, 0x69000
	s_addc_u32 s3, s53, 0
	global_load_dword v140, v180, s[2:3]
	global_load_dword v141, v180, s[2:3] offset:128
	s_add_u32 s2, s52, 0x6a000
	s_addc_u32 s3, s53, 0
	global_load_dword v142, v180, s[2:3]
	global_load_dword v143, v180, s[2:3] offset:128
	s_add_u32 s2, s52, 0x6b000
	s_addc_u32 s3, s53, 0
	global_load_dword v144, v180, s[2:3]
	global_load_dword v145, v180, s[2:3] offset:128
	s_waitcnt vmcnt(32)
	v_fmamk_f32 v50, v146, 0x3fd744fd, v50
	v_fmamk_f32 v34, v147, 0x3fd744fd, v34
	v_fmamk_f32 v51, v148, 0x3fd744fd, v51
	v_fmamk_f32 v35, v149, 0x3fd744fd, v35
	v_fmamk_f32 v52, v150, 0x3fd744fd, v52
	v_fmamk_f32 v36, v151, 0x3fd744fd, v36
	v_fmamk_f32 v53, v152, 0x3fd744fd, v53
	v_fmamk_f32 v37, v153, 0x3fd744fd, v37
	v_fmamk_f32 v54, v154, 0x3fd744fd, v54
	v_fmamk_f32 v38, v155, 0x3fd744fd, v38
	v_fmamk_f32 v55, v156, 0x3fd744fd, v55
	v_fmamk_f32 v39, v157, 0x3fd744fd, v39
	v_fmamk_f32 v56, v158, 0x3fd744fd, v56
	v_fmamk_f32 v40, v159, 0x3fd744fd, v40
	v_fmamk_f32 v57, v160, 0x3fd744fd, v57
	v_fmamk_f32 v41, v161, 0x3fd744fd, v41
	s_add_u32 s2, s52, 0x70000
	s_addc_u32 s3, s53, 0
	global_load_dword v146, v180, s[2:3]
	global_load_dword v147, v180, s[2:3] offset:128
	s_add_u32 s2, s52, 0x71000
	s_addc_u32 s3, s53, 0
	global_load_dword v148, v180, s[2:3]
	global_load_dword v149, v180, s[2:3] offset:128
	s_add_u32 s2, s52, 0x72000
	s_addc_u32 s3, s53, 0
	global_load_dword v150, v180, s[2:3]
	global_load_dword v151, v180, s[2:3] offset:128
	s_add_u32 s2, s52, 0x73000
	s_addc_u32 s3, s53, 0
	global_load_dword v152, v180, s[2:3]
	global_load_dword v153, v180, s[2:3] offset:128
	s_add_u32 s2, s52, 0x78000
	s_addc_u32 s3, s53, 0
	global_load_dword v154, v180, s[2:3]
	global_load_dword v155, v180, s[2:3] offset:128
	s_add_u32 s2, s52, 0x79000
	s_addc_u32 s3, s53, 0
	global_load_dword v156, v180, s[2:3]
	global_load_dword v157, v180, s[2:3] offset:128
	s_add_u32 s2, s52, 0x7a000
	s_addc_u32 s3, s53, 0
	global_load_dword v158, v180, s[2:3]
	global_load_dword v159, v180, s[2:3] offset:128
	s_add_u32 s2, s52, 0x7b000
	s_addc_u32 s3, s53, 0
	global_load_dword v160, v180, s[2:3]
	global_load_dword v161, v180, s[2:3] offset:128
	s_waitcnt vmcnt(32)
	v_fmamk_f32 v58, v162, 0x3fd744fd, v58
	v_fmamk_f32 v42, v163, 0x3fd744fd, v42
	v_fmamk_f32 v59, v164, 0x3fd744fd, v59
	v_fmamk_f32 v43, v165, 0x3fd744fd, v43
	v_fmamk_f32 v60, v166, 0x3fd744fd, v60
	v_fmamk_f32 v44, v167, 0x3fd744fd, v44
	v_fmamk_f32 v61, v168, 0x3fd744fd, v61
	v_fmamk_f32 v45, v169, 0x3fd744fd, v45
	v_fmamk_f32 v62, v170, 0x3fd744fd, v62
	v_fmamk_f32 v46, v171, 0x3fd744fd, v46
	v_fmamk_f32 v63, v172, 0x3fd744fd, v63
	v_fmamk_f32 v47, v173, 0x3fd744fd, v47
	v_fmamk_f32 v64, v174, 0x3fd744fd, v64
	v_fmamk_f32 v48, v175, 0x3fd744fd, v48
	v_fmamk_f32 v65, v176, 0x3fd744fd, v65
	v_fmamk_f32 v49, v177, 0x3fd744fd, v49
	s_waitcnt vmcnt(16)
;   __device__ __forceinline__ float* xr() const { return (float*)(ws() + OFF_xr); }
;   __device__ __forceinline__ half_t* u() const { return (half_t*)(ws() + OFF_u); }
; __device__ __forceinline__ void phase_outproj(const KP& p, char* smem, int* q, int xcc) {
;     ...
;         [&](int mi, int ni, int r, int row, int col, float v) {
;           const size_t xi = (size_t)(m0 + row) * DM + n0 + col;
;           ((float*)p.u())[xi] = ALPHA_F * p.xr()[xi] + v;
;         },
	v_fmamk_f32 v18, v130, 0x3fd744fd, v18
	v_fmamk_f32 v2, v131, 0x3fd744fd, v2
	v_fmamk_f32 v19, v132, 0x3fd744fd, v19
	v_fmamk_f32 v3, v133, 0x3fd744fd, v3
	v_fmamk_f32 v20, v134, 0x3fd744fd, v20
	v_fmamk_f32 v4, v135, 0x3fd744fd, v4
	v_fmamk_f32 v21, v136, 0x3fd744fd, v21
	v_fmamk_f32 v5, v137, 0x3fd744fd, v5
	v_fmamk_f32 v22, v138, 0x3fd744fd, v22
	v_fmamk_f32 v6, v139, 0x3fd744fd, v6
	v_fmamk_f32 v23, v140, 0x3fd744fd, v23
	v_fmamk_f32 v7, v141, 0x3fd744fd, v7
	v_fmamk_f32 v24, v142, 0x3fd744fd, v24
	v_fmamk_f32 v8, v143, 0x3fd744fd, v8
	v_fmamk_f32 v25, v144, 0x3fd744fd, v25
	v_fmamk_f32 v9, v145, 0x3fd744fd, v9
	s_waitcnt vmcnt(0)
	v_fmamk_f32 v26, v146, 0x3fd744fd, v26
	v_fmamk_f32 v10, v147, 0x3fd744fd, v10
	v_fmamk_f32 v27, v148, 0x3fd744fd, v27
	v_fmamk_f32 v11, v149, 0x3fd744fd, v11
	v_fmamk_f32 v28, v150, 0x3fd744fd, v28
	v_fmamk_f32 v12, v151, 0x3fd744fd, v12
	v_fmamk_f32 v29, v152, 0x3fd744fd, v29
	v_fmamk_f32 v13, v153, 0x3fd744fd, v13
	v_fmamk_f32 v30, v154, 0x3fd744fd, v30
	v_fmamk_f32 v14, v155, 0x3fd744fd, v14
	v_fmamk_f32 v31, v156, 0x3fd744fd, v31
	v_fmamk_f32 v15, v157, 0x3fd744fd, v15
	v_fmamk_f32 v32, v158, 0x3fd744fd, v32
	v_fmamk_f32 v16, v159, 0x3fd744fd, v16
	v_fmamk_f32 v33, v160, 0x3fd744fd, v33
	v_fmamk_f32 v17, v161, 0x3fd744fd, v17
	s_add_u32 s2, s42, 0x0
	s_addc_u32 s3, s43, 0
	global_store_dword v180, v114, s[2:3]
	global_store_dword v180, v98, s[2:3] offset:128
	s_add_u32 s2, s42, 0x1000
	s_addc_u32 s3, s43, 0
	global_store_dword v180, v115, s[2:3]
	global_store_dword v180, v99, s[2:3] offset:128
	s_add_u32 s2, s42, 0x2000
	s_addc_u32 s3, s43, 0
	global_store_dword v180, v116, s[2:3]
	global_store_dword v180, v100, s[2:3] offset:128
	s_add_u32 s2, s42, 0x3000
	s_addc_u32 s3, s43, 0
	global_store_dword v180, v117, s[2:3]
	global_store_dword v180, v101, s[2:3] offset:128
	s_add_u32 s2, s42, 0x8000
	s_addc_u32 s3, s43, 0
	global_store_dword v180, v118, s[2:3]
	global_store_dword v180, v102, s[2:3] offset:128
	s_add_u32 s2, s42, 0x9000
	s_addc_u32 s3, s43, 0
	global_store_dword v180, v119, s[2:3]
	global_store_dword v180, v103, s[2:3] offset:128
	s_add_u32 s2, s42, 0xa000
	s_addc_u32 s3, s43, 0
	global_store_dword v180, v120, s[2:3]
	global_store_dword v180, v104, s[2:3] offset:128
	s_add_u32 s2, s42, 0xb000
	s_addc_u32 s3, s43, 0
	global_store_dword v180, v121, s[2:3]
	global_store_dword v180, v105, s[2:3] offset:128
	s_add_u32 s2, s42, 0x10000
	s_addc_u32 s3, s43, 0
	global_store_dword v180, v122, s[2:3]
	global_store_dword v180, v106, s[2:3] offset:128
	s_add_u32 s2, s42, 0x11000
	s_addc_u32 s3, s43, 0
	global_store_dword v180, v123, s[2:3]
	global_store_dword v180, v107, s[2:3] offset:128
	s_add_u32 s2, s42, 0x12000
	s_addc_u32 s3, s43, 0
	global_store_dword v180, v124, s[2:3]
	global_store_dword v180, v108, s[2:3] offset:128
	s_add_u32 s2, s42, 0x13000
	s_addc_u32 s3, s43, 0
	global_store_dword v180, v125, s[2:3]
	global_store_dword v180, v109, s[2:3] offset:128
	s_add_u32 s2, s42, 0x18000
	s_addc_u32 s3, s43, 0
	global_store_dword v180, v126, s[2:3]
	global_store_dword v180, v110, s[2:3] offset:128
	s_add_u32 s2, s42, 0x19000
	s_addc_u32 s3, s43, 0
	global_store_dword v180, v127, s[2:3]
	global_store_dword v180, v111, s[2:3] offset:128
	s_add_u32 s2, s42, 0x1a000
	s_addc_u32 s3, s43, 0
	global_store_dword v180, v128, s[2:3]
	global_store_dword v180, v112, s[2:3] offset:128
	s_add_u32 s2, s42, 0x1b000
	s_addc_u32 s3, s43, 0
	global_store_dword v180, v129, s[2:3]
	global_store_dword v180, v113, s[2:3] offset:128
	s_add_u32 s2, s42, 0x20000
	s_addc_u32 s3, s43, 0
	global_store_dword v180, v82, s[2:3]
	global_store_dword v180, v66, s[2:3] offset:128
	s_add_u32 s2, s42, 0x21000
	s_addc_u32 s3, s43, 0
	global_store_dword v180, v83, s[2:3]
	global_store_dword v180, v67, s[2:3] offset:128
	s_add_u32 s2, s42, 0x22000
	s_addc_u32 s3, s43, 0
	global_store_dword v180, v84, s[2:3]
	global_store_dword v180, v68, s[2:3] offset:128
	s_add_u32 s2, s42, 0x23000
	s_addc_u32 s3, s43, 0
	global_store_dword v180, v85, s[2:3]
	global_store_dword v180, v69, s[2:3] offset:128
	s_add_u32 s2, s42, 0x28000
	s_addc_u32 s3, s43, 0
	global_store_dword v180, v86, s[2:3]
	global_store_dword v180, v70, s[2:3] offset:128
	s_add_u32 s2, s42, 0x29000
	s_addc_u32 s3, s43, 0
	global_store_dword v180, v87, s[2:3]
	global_store_dword v180, v71, s[2:3] offset:128
	s_add_u32 s2, s42, 0x2a000
	s_addc_u32 s3, s43, 0
	global_store_dword v180, v88, s[2:3]
	global_store_dword v180, v72, s[2:3] offset:128
	s_add_u32 s2, s42, 0x2b000
	s_addc_u32 s3, s43, 0
	global_store_dword v180, v89, s[2:3]
	global_store_dword v180, v73, s[2:3] offset:128
	s_add_u32 s2, s42, 0x30000
	s_addc_u32 s3, s43, 0
	global_store_dword v180, v90, s[2:3]
	global_store_dword v180, v74, s[2:3] offset:128
	s_add_u32 s2, s42, 0x31000
	s_addc_u32 s3, s43, 0
	global_store_dword v180, v91, s[2:3]
	global_store_dword v180, v75, s[2:3] offset:128
	s_add_u32 s2, s42, 0x32000
	s_addc_u32 s3, s43, 0
	global_store_dword v180, v92, s[2:3]
	global_store_dword v180, v76, s[2:3] offset:128
	s_add_u32 s2, s42, 0x33000
	s_addc_u32 s3, s43, 0
;   __device__ __forceinline__ const float* x() const { return (const float*)(const __attribute__((address_space(1))) float*)kp[0]; }
;   __device__ __forceinline__ float* xr() const { return (float*)(ws() + OFF_xr); }
;   __device__ __forceinline__ half_t* u() const { return (half_t*)(ws() + OFF_u); }
; template <class F>
; __device__ __forceinline__ void xcd_schedule(int* q, int xcc, int ngroups, int gsize, char* smem, F f) {
;     ...
;     for (;;) {
;       if (threadIdx.x == 0) *s_item = atomicAdd(&q[y], 1);
;       __syncthreads();
;       const int i = __builtin_amdgcn_readfirstlane(*s_item);
;       __syncthreads();
;       const int grp = (i / gsize) * 8 + y;
;       if (grp >= ngroups) {
;         if (threadIdx.x == 0) __hip_atomic_store(&flags[y], 1, __ATOMIC_RELAXED, __HIP_MEMORY_SCOPE_AGENT);
;         break;
;       }
;       f(grp, i % gsize);
; __device__ __forceinline__ void phase_outproj(const KP& p, char* smem, int* q, int xcc) {
;     ...
;         [&](int mi, int ni, int r, int row, int col, float v) {
;           const size_t xi = (size_t)(m0 + row) * DM + n0 + col;
;           ((float*)p.u())[xi] = ALPHA_F * p.xr()[xi] + v;
;         },
	global_store_dword v180, v93, s[2:3]
	global_store_dword v180, v77, s[2:3] offset:128
	s_add_u32 s2, s42, 0x38000
	s_addc_u32 s3, s43, 0
	global_store_dword v180, v94, s[2:3]
	global_store_dword v180, v78, s[2:3] offset:128
	s_add_u32 s2, s42, 0x39000
	s_addc_u32 s3, s43, 0
	global_store_dword v180, v95, s[2:3]
	global_store_dword v180, v79, s[2:3] offset:128
	s_add_u32 s2, s42, 0x3a000
	s_addc_u32 s3, s43, 0
	global_store_dword v180, v96, s[2:3]
	global_store_dword v180, v80, s[2:3] offset:128
	s_add_u32 s2, s42, 0x3b000
	s_addc_u32 s3, s43, 0
	global_store_dword v180, v97, s[2:3]
	global_store_dword v180, v81, s[2:3] offset:128
	s_add_u32 s2, s42, 0x40000
	s_addc_u32 s3, s43, 0
	global_store_dword v180, v50, s[2:3]
	global_store_dword v180, v34, s[2:3] offset:128
	s_add_u32 s2, s42, 0x41000
	s_addc_u32 s3, s43, 0
	global_store_dword v180, v51, s[2:3]
	global_store_dword v180, v35, s[2:3] offset:128
	s_add_u32 s2, s42, 0x42000
	s_addc_u32 s3, s43, 0
	global_store_dword v180, v52, s[2:3]
	global_store_dword v180, v36, s[2:3] offset:128
	s_add_u32 s2, s42, 0x43000
	s_addc_u32 s3, s43, 0
	global_store_dword v180, v53, s[2:3]
	global_store_dword v180, v37, s[2:3] offset:128
	s_add_u32 s2, s42, 0x48000
	s_addc_u32 s3, s43, 0
	global_store_dword v180, v54, s[2:3]
	global_store_dword v180, v38, s[2:3] offset:128
	s_add_u32 s2, s42, 0x49000
	s_addc_u32 s3, s43, 0
	global_store_dword v180, v55, s[2:3]
	global_store_dword v180, v39, s[2:3] offset:128
	s_add_u32 s2, s42, 0x4a000
	s_addc_u32 s3, s43, 0
	global_store_dword v180, v56, s[2:3]
	global_store_dword v180, v40, s[2:3] offset:128
	s_add_u32 s2, s42, 0x4b000
	s_addc_u32 s3, s43, 0
	global_store_dword v180, v57, s[2:3]
	global_store_dword v180, v41, s[2:3] offset:128
	s_add_u32 s2, s42, 0x50000
	s_addc_u32 s3, s43, 0
	global_store_dword v180, v58, s[2:3]
	global_store_dword v180, v42, s[2:3] offset:128
	s_add_u32 s2, s42, 0x51000
	s_addc_u32 s3, s43, 0
	global_store_dword v180, v59, s[2:3]
	global_store_dword v180, v43, s[2:3] offset:128
	s_add_u32 s2, s42, 0x52000
	s_addc_u32 s3, s43, 0
	global_store_dword v180, v60, s[2:3]
	global_store_dword v180, v44, s[2:3] offset:128
	s_add_u32 s2, s42, 0x53000
	s_addc_u32 s3, s43, 0
	global_store_dword v180, v61, s[2:3]
	global_store_dword v180, v45, s[2:3] offset:128
	s_add_u32 s2, s42, 0x58000
	s_addc_u32 s3, s43, 0
	global_store_dword v180, v62, s[2:3]
	global_store_dword v180, v46, s[2:3] offset:128
	s_add_u32 s2, s42, 0x59000
	s_addc_u32 s3, s43, 0
	global_store_dword v180, v63, s[2:3]
	global_store_dword v180, v47, s[2:3] offset:128
	s_add_u32 s2, s42, 0x5a000
	s_addc_u32 s3, s43, 0
	global_store_dword v180, v64, s[2:3]
	global_store_dword v180, v48, s[2:3] offset:128
	s_add_u32 s2, s42, 0x5b000
	s_addc_u32 s3, s43, 0
	global_store_dword v180, v65, s[2:3]
	global_store_dword v180, v49, s[2:3] offset:128
	s_add_u32 s2, s42, 0x60000
	s_addc_u32 s3, s43, 0
	global_store_dword v180, v18, s[2:3]
	global_store_dword v180, v2, s[2:3] offset:128
	s_add_u32 s2, s42, 0x61000
	s_addc_u32 s3, s43, 0
	global_store_dword v180, v19, s[2:3]
	global_store_dword v180, v3, s[2:3] offset:128
	s_add_u32 s2, s42, 0x62000
	s_addc_u32 s3, s43, 0
	global_store_dword v180, v20, s[2:3]
	global_store_dword v180, v4, s[2:3] offset:128
	s_add_u32 s2, s42, 0x63000
	s_addc_u32 s3, s43, 0
	global_store_dword v180, v21, s[2:3]
	global_store_dword v180, v5, s[2:3] offset:128
	s_add_u32 s2, s42, 0x68000
	s_addc_u32 s3, s43, 0
	global_store_dword v180, v22, s[2:3]
	global_store_dword v180, v6, s[2:3] offset:128
	s_add_u32 s2, s42, 0x69000
	s_addc_u32 s3, s43, 0
	global_store_dword v180, v23, s[2:3]
	global_store_dword v180, v7, s[2:3] offset:128
	s_add_u32 s2, s42, 0x6a000
	s_addc_u32 s3, s43, 0
	global_store_dword v180, v24, s[2:3]
	global_store_dword v180, v8, s[2:3] offset:128
	s_add_u32 s2, s42, 0x6b000
	s_addc_u32 s3, s43, 0
	global_store_dword v180, v25, s[2:3]
	global_store_dword v180, v9, s[2:3] offset:128
	s_add_u32 s2, s42, 0x70000
	s_addc_u32 s3, s43, 0
	global_store_dword v180, v26, s[2:3]
	global_store_dword v180, v10, s[2:3] offset:128
	s_add_u32 s2, s42, 0x71000
	s_addc_u32 s3, s43, 0
	global_store_dword v180, v27, s[2:3]
	global_store_dword v180, v11, s[2:3] offset:128
	s_add_u32 s2, s42, 0x72000
	s_addc_u32 s3, s43, 0
	global_store_dword v180, v28, s[2:3]
	global_store_dword v180, v12, s[2:3] offset:128
	s_add_u32 s2, s42, 0x73000
	s_addc_u32 s3, s43, 0
	global_store_dword v180, v29, s[2:3]
	global_store_dword v180, v13, s[2:3] offset:128
	s_add_u32 s2, s42, 0x78000
	s_addc_u32 s3, s43, 0
	global_store_dword v180, v30, s[2:3]
	global_store_dword v180, v14, s[2:3] offset:128
	s_add_u32 s2, s42, 0x79000
	s_addc_u32 s3, s43, 0
	global_store_dword v180, v31, s[2:3]
	global_store_dword v180, v15, s[2:3] offset:128
	s_add_u32 s2, s42, 0x7a000
	s_addc_u32 s3, s43, 0
	global_store_dword v180, v32, s[2:3]
	global_store_dword v180, v16, s[2:3] offset:128
	s_add_u32 s2, s42, 0x7b000
	s_addc_u32 s3, s43, 0
	global_store_dword v180, v33, s[2:3]
	global_store_dword v180, v17, s[2:3] offset:128
	s_branch .LBB0_1805

;   __device__ __forceinline__ const float* x() const { return (const float*)(const __attribute__((address_space(1))) float*)kp[0]; }
;   __device__ __forceinline__ const float* wo() const { return (const float*)(const __attribute__((address_space(1))) float*)kp[15]; }
;   __device__ __forceinline__ half_t* woT() const { return (half_t*)(ws() + OFF_woT); }
; template <class CM>
; __device__ __forceinline__ void tconv_tile(const float* __restrict__ src, int lds_, half_t* __restrict__ dst, int ldd,
;                                            int n0, int k0, CM cmap, char* smem) {
;   float* t = (float*)smem;
;   int tid = threadIdx.x;
;   asm volatile("" : "+v"(tid));
;   {
;     const int n = tid & 63;
;     const int c = cmap(n0 + n);
;     float tv[16];
; #pragma unroll
;     for (int i = 0; i < 16; ++i) {
;       const int k = (tid >> 6) + 4 * i;
;       tv[i] = (c >= 0) ? src[(size_t)(k0 + k) * lds_ + c] : 0.f;
;     }
; #pragma unroll
;     for (int i = 0; i < 16; ++i) {
;       const int k = (tid >> 6) + 4 * i;
;       t[k * 65 + n] = tv[i];
;     }
;   }
;   __syncthreads();
; #pragma unroll
;   for (int i = 0; i < 2; ++i) {
;     const int idx = tid + 256 * i;
;     const int n = idx >> 3, kc = (idx & 7) * 8;
;     h8 v;
; #pragma unroll
;     for (int j = 0; j < 8; ++j) v[j] = (half_t)t[(kc + j) * 65 + n];
;     *(h8*)&dst[(size_t)(n0 + n) * ldd + k0 + kc] = v;
;   }
;   __syncthreads();
; }
; __device__ __forceinline__ void prep_weights(const KP& p, int l, char* smem) {
;     ...
;     } else if (it < 1856 + 384 + 256) {
;       const int j = it - 1856 - 384;
;       const int nt = j >> 4, kt = j & 15;
;       tconv_tile(p.wo() + (size_t)l * DM * DM, DM, p.woT(), DM, nt * 64, kt * 64, [](int n) { return n; }, smem);
.LBB0_1891:
	s_andn2_b64 vcc, exec, s[2:3]
	s_cbranch_vccnz .LBB0_1893
	s_load_dwordx2 s[14:15], s[10:11], 0x78
	s_load_dwordx2 s[2:3], s[10:11], 0x98
	v_mov_b32_e32 v18, v224
	s_waitcnt lgkmcnt(0)
	s_add_u32 s14, s14, s18
	s_addc_u32 s15, s15, s19
	s_lshl_b32 s8, s1, 2
	s_lshl_b32 s30, s1, 6
	s_and_b32 s8, s8, 0x3fc0
	s_and_b32 s30, s30, 0x3c0
	v_ashrrev_i32_e32 v11, 6, v18
	s_addk_i32 s8, 0xdd00
	v_and_b32_e32 v10, 63, v18
	v_add_u32_e32 v6, s30, v11
	v_or_b32_e32 v0, s8, v10
	v_ashrrev_i32_e32 v7, 31, v6
	v_lshl_add_u64 v[8:9], v[0:1], 2, s[14:15]
	v_lshlrev_b64 v[6:7], 12, v[6:7]
	v_lshl_add_u64 v[6:7], v[8:9], 0, v[6:7]
	s_movk_i32 s14, 0x4000
	v_add_co_u32_e32 v8, vcc, s14, v6
	global_load_dword v0, v[6:7], off
	s_nop 0
	v_addc_co_u32_e32 v9, vcc, 0, v7, vcc
	global_load_dword v14, v[8:9], off
	v_add_co_u32_e32 v8, vcc, s73, v6
	s_mov_b32 s14, 0xc000
	s_nop 0
	v_addc_co_u32_e32 v9, vcc, 0, v7, vcc
	global_load_dword v15, v[8:9], off
	v_add_co_u32_e32 v8, vcc, s14, v6
	s_mov_b32 s14, 0x14000
	s_nop 0
	v_addc_co_u32_e32 v9, vcc, 0, v7, vcc
	global_load_dword v16, v[8:9], off
	v_add_co_u32_e32 v8, vcc, s72, v6
	s_nop 1
	v_addc_co_u32_e32 v9, vcc, 0, v7, vcc
	global_load_dword v17, v[8:9], off
	v_add_co_u32_e32 v8, vcc, s14, v6
	s_mov_b32 s14, 0x1c000
	s_nop 0
	v_addc_co_u32_e32 v9, vcc, 0, v7, vcc
	global_load_dword v19, v[8:9], off
	v_add_co_u32_e32 v8, vcc, s77, v6
	s_nop 1
	v_addc_co_u32_e32 v9, vcc, 0, v7, vcc
	global_load_dword v20, v[8:9], off
	v_add_co_u32_e32 v8, vcc, s14, v6
	s_mov_b32 s14, 0x20000
	s_nop 0
	v_addc_co_u32_e32 v9, vcc, 0, v7, vcc
	global_load_dword v21, v[8:9], off
	v_add_co_u32_e32 v8, vcc, s14, v6
	s_mov_b32 s14, 0x24000
	s_nop 0
	v_addc_co_u32_e32 v9, vcc, 0, v7, vcc
	global_load_dword v22, v[8:9], off
	v_add_co_u32_e32 v8, vcc, s14, v6
	s_mov_b32 s14, 0x28000
	s_nop 0
	v_addc_co_u32_e32 v9, vcc, 0, v7, vcc
	global_load_dword v23, v[8:9], off
	v_add_co_u32_e32 v8, vcc, s14, v6
	s_mov_b32 s14, 0x2c000
	s_nop 0
	v_addc_co_u32_e32 v9, vcc, 0, v7, vcc
	global_load_dword v24, v[8:9], off
	v_add_co_u32_e32 v8, vcc, s14, v6
	s_mov_b32 s14, 0x30000
	s_nop 0
	v_addc_co_u32_e32 v9, vcc, 0, v7, vcc
	global_load_dword v25, v[8:9], off
	v_add_co_u32_e32 v8, vcc, s14, v6
	s_mov_b32 s14, 0x34000
	s_nop 0
	v_addc_co_u32_e32 v9, vcc, 0, v7, vcc
	global_load_dword v26, v[8:9], off
	v_add_co_u32_e32 v8, vcc, s14, v6
	s_mov_b32 s14, 0x38000
	s_nop 0
	v_addc_co_u32_e32 v9, vcc, 0, v7, vcc
	global_load_dword v27, v[8:9], off
	v_add_co_u32_e32 v8, vcc, s14, v6
	s_mov_b32 s14, 0x3c000
	s_nop 0
	v_addc_co_u32_e32 v9, vcc, 0, v7, vcc
	v_add_co_u32_e32 v6, vcc, s14, v6
	global_load_dword v8, v[8:9], off
	s_nop 0
	v_addc_co_u32_e32 v7, vcc, 0, v7, vcc
	global_load_dword v6, v[6:7], off
	s_movk_i32 s14, 0x104
	v_mul_lo_u32 v7, v11, s14
	v_lshl_add_u32 v7, v10, 2, v7
	s_waitcnt vmcnt(15)
	ds_write_b32 v7, v0
	s_waitcnt vmcnt(14)
	ds_write_b32 v7, v14 offset:1040
	s_waitcnt vmcnt(13)
	ds_write_b32 v7, v15 offset:2080
	s_waitcnt vmcnt(12)
	ds_write_b32 v7, v16 offset:3120
	s_waitcnt vmcnt(11)
	ds_write_b32 v7, v17 offset:4160
	s_waitcnt vmcnt(10)
	ds_write_b32 v7, v19 offset:5200
	s_waitcnt vmcnt(9)
	ds_write_b32 v7, v20 offset:6240
	s_waitcnt vmcnt(8)
	ds_write_b32 v7, v21 offset:7280
	s_waitcnt vmcnt(7)
	ds_write_b32 v7, v22 offset:8320
	s_waitcnt vmcnt(6)
	ds_write_b32 v7, v23 offset:9360
	s_waitcnt vmcnt(5)
	ds_write_b32 v7, v24 offset:10400
	s_waitcnt vmcnt(4)
	ds_write_b32 v7, v25 offset:11440
	s_waitcnt vmcnt(3)
	ds_write_b32 v7, v26 offset:12480
	s_waitcnt vmcnt(2)
	ds_write_b32 v7, v27 offset:13520
	s_waitcnt vmcnt(1)
	ds_write_b32 v7, v8 offset:14560
	s_waitcnt vmcnt(0)
	ds_write_b32 v7, v6 offset:15600
	v_lshlrev_b32_e32 v0, 3, v18
	s_lshr_b32 s14, s30, 5
	s_lshl_b32 s14, s14, 16
	v_and_b32_e32 v8, 56, v0
	s_add_u32 s2, s2, s14
	s_addc_u32 s3, s3, 0
	v_lshrrev_b32_e32 v0, 5, v8
	v_and_b32_e32 v6, 31, v8
	v_lshlrev_b32_e32 v0, 16, v0
	v_lshl_add_u32 v0, v6, 1, v0
	v_lshl_add_u64 v[6:7], s[2:3], 0, v[0:1]
	v_mul_u32_u24_e32 v0, 0x104, v8
	v_ashrrev_i32_e32 v19, 3, v18
	s_mov_b64 s[2:3], 0x15980000
	v_lshl_add_u32 v8, v19, 2, v0
	s_waitcnt lgkmcnt(0)
	s_barrier
	v_lshl_add_u64 v[10:11], v[6:7], 0, s[2:3]
	ds_read2_b32 v[14:15], v8 offset1:65
	ds_read2_b32 v[6:7], v8 offset0:130 offset1:195
	v_add_u32_e32 v8, 0x400, v8
	ds_read2_b32 v[16:17], v8 offset0:4 offset1:69
	ds_read2_b32 v[8:9], v8 offset0:134 offset1:199
	s_waitcnt lgkmcnt(2)
	v_cvt_pk_f16_f32 v7, v6, v7
	v_cvt_pk_f16_f32 v6, v14, v15
	v_add_u32_e32 v14, s8, v19
	v_ashrrev_i32_e32 v15, 31, v14
	v_lshlrev_b64 v[14:15], 6, v[14:15]
	s_waitcnt lgkmcnt(0)
	v_cvt_pk_f16_f32 v9, v8, v9
	v_cvt_pk_f16_f32 v8, v16, v17
	v_lshl_add_u64 v[14:15], v[10:11], 0, v[14:15]
	global_store_dwordx4 v[14:15], v[6:9], off
	s_nop 1
	v_add_u32_e32 v6, 0x100, v18
	v_ashrrev_i32_e32 v18, 3, v6
	v_lshl_add_u32 v0, v18, 2, v0
	ds_read2_b32 v[14:15], v0 offset1:65
	ds_read2_b32 v[6:7], v0 offset0:130 offset1:195
	v_add_u32_e32 v0, 0x400, v0
	ds_read2_b32 v[16:17], v0 offset0:4 offset1:69
	ds_read2_b32 v[8:9], v0 offset0:134 offset1:199
	s_waitcnt lgkmcnt(2)
	v_cvt_pk_f16_f32 v7, v6, v7
	v_cvt_pk_f16_f32 v6, v14, v15
	v_add_u32_e32 v14, s8, v18
	v_ashrrev_i32_e32 v15, 31, v14
	v_lshlrev_b64 v[14:15], 6, v[14:15]
	s_waitcnt lgkmcnt(0)
	v_cvt_pk_f16_f32 v9, v8, v9
	v_cvt_pk_f16_f32 v8, v16, v17
	v_lshl_add_u64 v[10:11], v[10:11], 0, v[14:15]
	global_store_dwordx4 v[10:11], v[6:9], off
	s_barrier
